# v34 + zpost fast path: two register sets, next token's 17 loads issued before the current token is processed, counted vmcnt leaves the 13 stores in flight
# speedup vs baseline: 1.0018x; 1.0018x over previous
; __global__ void __launch_bounds__(512, 2) fwd_kernel(Args a) {
;     ...
;                 for (int m = gw; m < MTOK; m += NGW) {
;                     bf16_t* z = Z + (size_t)m * ZC; const int pos = m & (SEQ - 1), rowp = pos >> 6, colp = pos & 63;
;                     const int grp = lane >> 2, ia = lane & 3, basea = (grp < 8 ? 0 : 256) + (grp & 7) * 32;
;                     const bf16_t ra1 = z[basea + ia], ra2 = z[basea + 4 + ia];
;                     const u32x2 wq = *(const u32x2*)(z + 768 + 4 * lane);
;                     const unsigned wkv = *(const unsigned*)(z + 1024 + 2 * lane);
;                     const bf16_t rk1 = z[1152 + (lane & 15)], rk2 = z[1168 + (lane & 15)];
;                     bf16_t rh[8];
; #pragma unroll
;                     for (int hd = 0; hd < 8; ++hd) rh[hd] = z[(hd < 6 ? 1184 + hd * 64 : 1568 + (hd - 6) * 64) + lane];
;                     const f32x2_t csa = *(const f32x2_t*)(taba + (size_t)(pos * 4 + ia) * 2);
;                     const f32x2_t csk = *(const f32x2_t*)(tab32 + (size_t)(pos * 16 + (lane & 15)) * 2);
;                     const int pp = lane < 32 ? rowp : colp; const f32x2_t cs = *(const f32x2_t*)(tab32 + (size_t)(pp * 16 + (lane & 15)) * 2);
;                     asm volatile("" ::: "memory");
.LBB0_310:
	v_readlane_b32 s4, v252, 39
	v_readlane_b32 s5, v252, 40
	s_and_b64 vcc, exec, s[4:5]
	s_cbranch_vccz .LBB0_318
	v_readlane_b32 s0, v252, 38
	v_readlane_b32 s4, v252, 36
	s_cmp_gt_i32 s0, 0
	s_mov_b64 s[6:7], -1
	v_readlane_b32 s5, v252, 37
	s_cbranch_scc0 .LBB0_321
	s_cmp_gt_i32 s0, 1
	s_mov_b64 s[4:5], -1
	s_cbranch_scc0 .LBB0_320
	s_lshl_b32 s0, s62, 3
	s_add_i32 s22, s0, s57
	s_brev_b32 s16, 60
	v_mbcnt_lo_u32_b32 v0, -1, 0
	v_mbcnt_hi_u32_b32 v0, -1, v0
	s_cmp_gt_i32 s22, 0x13fff
	v_add_u32_e32 v2, s33, v0
	s_mov_b32 s17, 0x3b800000
	s_mov_b32 s18, 0x3c800000
	s_cbranch_scc1 .LBB0_319
	v_readlane_b32 s8, v252, 17
	v_readlane_b32 s9, v252, 18
	s_load_dwordx4 s[4:7], s[8:9], 0x78
	s_lshl_b32 s8, s69, 6
	s_ashr_i32 s9, s8, 31
	s_lshl_b64 s[8:9], s[8:9], 2
	v_and_b32_e32 v5, 63, v2
	s_waitcnt lgkmcnt(0)
	s_add_u32 s4, s4, s8
	s_addc_u32 s5, s5, s9
	v_lshlrev_b32_e32 v0, 2, v5
	global_load_dword v14, v0, s[4:5]
	s_add_u32 s4, s6, s8
	s_addc_u32 s5, s7, s9
	global_load_dword v28, v0, s[4:5]
	v_and_b32_e32 v4, 3, v2
	v_lshlrev_b32_e32 v6, 3, v2
	v_mov_b32_e32 v3, v1
	v_lshlrev_b32_e32 v7, 1, v2
	v_and_b32_e32 v8, 16, v2
	v_lshlrev_b32_e32 v2, 1, v5
	s_movk_i32 s4, 0x1e0
	v_and_or_b32 v12, v6, s4, v4
	v_mad_i64_i32 v[2:3], s[4:5], s22, v223, v[2:3]
	s_ashr_i32 s23, s22, 31
	s_lshl_b64 s[4:5], s[22:23], 6
	s_add_u32 s4, s4, 0x4b00000
	s_addc_u32 s5, s5, 0
	s_ashr_i32 s55, s54, 31
	s_mul_i32 s13, s22, 0xe40
	s_lshl_b64 s[76:77], s[54:55], 6
	s_mul_hi_i32 s0, s22, 0xe40
	v_and_b32_e32 v29, 30, v7
	v_lshl_add_u64 v[6:7], s[4:5], 0, v[0:1]
	s_add_u32 s4, s13, 0x19000800
	s_addc_u32 s5, s0, 0
	v_cmp_eq_u32_e64 s[10:11], 0, v8
	v_lshl_add_u64 v[8:9], s[4:5], 0, v[0:1]
	s_add_u32 s4, s13, 0x19000600
	v_lshlrev_b32_e32 v0, 3, v5
	s_addc_u32 s5, s0, 0
	v_lshlrev_b32_e32 v15, 1, v4
	v_lshl_add_u64 v[10:11], s[4:5], 0, v[0:1]
	v_lshlrev_b32_e32 v0, 1, v12
	s_mul_hi_i32 s71, s54, 0xe40
	s_mul_i32 s70, s54, 0xe40
	v_cmp_gt_u32_e64 s[6:7], 32, v5
	v_cmp_gt_u32_e64 s[8:9], 16, v5
	v_or_b32_e32 v4, s13, v29
	s_movk_i32 s13, 0x7fff
	v_mad_i64_i32 v[12:13], s[4:5], s22, v223, v[0:1]
	v_mov_b32_e32 v5, s0
	v_lshlrev_b32_e32 v30, 2, v15
	s_waitcnt vmcnt(0)
	v_mul_f32_e32 v0, 0x3e38aa3b, v14
	s_cmpk_lg_i32 s54, 0x800
	s_cbranch_scc1 .LBB0_316
	s_movk_i32 s100, 20
	v_readlane_b32 s36, v252, 21
	v_readlane_b32 s38, v252, 23
	v_readlane_b32 s39, v252, 24
	s_and_b32 s0, s22, 0x1fff
	v_readlane_b32 s14, v252, 19
	v_lshl_add_u64 v[14:15], s[38:39], 0, v[4:5]
	v_add_co_u32_e32 v14, vcc, 0x19000000, v14
	v_lshl_add_u64 v[22:23], s[38:39], 0, v[10:11]
	v_lshl_add_u64 v[18:19], s[38:39], 0, v[8:9]
	v_addc_co_u32_e32 v15, vcc, 0, v15, vcc
	v_lshl_add_u64 v[16:17], s[38:39], 0, v[2:3]
	global_load_dwordx2 v[24:25], v[22:23], off
	global_load_dword v41, v[18:19], off
	global_load_ushort v39, v[14:15], off offset:2304
	global_load_ushort v40, v[14:15], off offset:2336
	v_add_co_u32_e32 v14, vcc, 0x19000000, v16
	v_readlane_b32 s15, v252, 20
	s_nop 0
	v_addc_co_u32_e32 v15, vcc, 0, v17, vcc
	global_load_ushort v38, v[14:15], off offset:2368
	global_load_ushort v37, v[14:15], off offset:2496
	global_load_ushort v36, v[14:15], off offset:2624
	global_load_ushort v35, v[14:15], off offset:2752
	global_load_ushort v34, v[14:15], off offset:2880
	global_load_ushort v33, v[14:15], off offset:3008
	global_load_ushort v32, v[14:15], off offset:3136
	global_load_ushort v31, v[14:15], off offset:3264
	v_lshl_or_b32 v14, s0, 5, v30
	global_load_dwordx2 v[26:27], v14, s[14:15]
	v_lshlrev_b32_e32 v14, 2, v29
	s_bfe_u32 s4, s22, 0x70006
	s_and_b32 s5, s22, 63
	v_lshl_or_b32 v15, s0, 7, v14
	v_lshl_add_u64 v[42:43], s[38:39], 0, v[12:13]
	global_load_dwordx2 v[20:21], v15, s[66:67]
	v_mov_b32_e32 v15, s5
	v_mov_b32_e32 v44, s4
	s_mov_b32 s0, 0x19000000
	v_cndmask_b32_e64 v15, v15, v44, s[6:7]
	v_add_co_u32_e32 v42, vcc, s0, v42
	v_lshl_or_b32 v14, v15, 7, v14
	s_nop 0
	v_addc_co_u32_e32 v43, vcc, 0, v43, vcc
	global_load_dwordx2 v[14:15], v14, s[66:67]
	s_nop 0
	global_load_ushort v44, v[42:43], off
	global_load_ushort v45, v[42:43], off offset:8
	v_readlane_b32 s37, v252, 22
	s_add_i32 s22, s22, s54
	v_lshl_add_u64 v[8:9], v[8:9], 0, s[70:71]
	v_lshl_add_u64 v[10:11], v[10:11], 0, s[70:71]
	v_lshl_add_u64 v[2:3], v[2:3], 0, s[70:71]
	v_lshl_add_u64 v[12:13], v[12:13], 0, s[70:71]
	v_lshl_add_u64 v[4:5], v[4:5], 0, s[70:71]
	v_readlane_b32 s36, v252, 21
	v_readlane_b32 s38, v252, 23
	v_readlane_b32 s39, v252, 24
	s_and_b32 s0, s22, 0x1fff
	v_readlane_b32 s14, v252, 19
	v_lshl_add_u64 v[64:65], s[38:39], 0, v[4:5]
	v_add_co_u32_e32 v64, vcc, 0x19000000, v64
	v_lshl_add_u64 v[72:73], s[38:39], 0, v[10:11]
	v_lshl_add_u64 v[68:69], s[38:39], 0, v[8:9]
	v_addc_co_u32_e32 v65, vcc, 0, v65, vcc
	v_lshl_add_u64 v[66:67], s[38:39], 0, v[2:3]
	global_load_dwordx2 v[74:75], v[72:73], off
	global_load_dword v91, v[68:69], off
	global_load_ushort v89, v[64:65], off offset:2304
	global_load_ushort v90, v[64:65], off offset:2336
	v_add_co_u32_e32 v64, vcc, 0x19000000, v66
	v_readlane_b32 s15, v252, 20
	s_nop 0
	v_addc_co_u32_e32 v65, vcc, 0, v67, vcc
	global_load_ushort v88, v[64:65], off offset:2368
	global_load_ushort v87, v[64:65], off offset:2496
	global_load_ushort v86, v[64:65], off offset:2624
	global_load_ushort v85, v[64:65], off offset:2752
	global_load_ushort v84, v[64:65], off offset:2880
	global_load_ushort v83, v[64:65], off offset:3008
	global_load_ushort v82, v[64:65], off offset:3136
	global_load_ushort v81, v[64:65], off offset:3264
	v_lshl_or_b32 v64, s0, 5, v30
	global_load_dwordx2 v[76:77], v64, s[14:15]
	v_lshlrev_b32_e32 v64, 2, v29
	s_bfe_u32 s4, s22, 0x70006
	s_and_b32 s5, s22, 63
	v_lshl_or_b32 v65, s0, 7, v64
	v_lshl_add_u64 v[92:93], s[38:39], 0, v[12:13]
	global_load_dwordx2 v[70:71], v65, s[66:67]
	v_mov_b32_e32 v65, s5
	v_mov_b32_e32 v94, s4
	s_mov_b32 s0, 0x19000000
	v_cndmask_b32_e64 v65, v65, v94, s[6:7]
	v_add_co_u32_e32 v92, vcc, s0, v92
	v_lshl_or_b32 v64, v65, 7, v64
	s_nop 0
	v_addc_co_u32_e32 v93, vcc, 0, v93, vcc
	global_load_dwordx2 v[64:65], v64, s[66:67]
	s_nop 0
	global_load_ushort v94, v[92:93], off
	global_load_ushort v95, v[92:93], off offset:8
	v_readlane_b32 s37, v252, 22
	s_add_i32 s22, s22, s54
	v_lshl_add_u64 v[8:9], v[8:9], 0, s[70:71]
	v_lshl_add_u64 v[10:11], v[10:11], 0, s[70:71]
	v_lshl_add_u64 v[2:3], v[2:3], 0, s[70:71]
	v_lshl_add_u64 v[12:13], v[12:13], 0, s[70:71]
	v_lshl_add_u64 v[4:5], v[4:5], 0, s[70:71]
	s_waitcnt vmcnt(17)
	s_branch .Lzp_CA
; __device__ __forceinline__ float bf2f(bf16_t v) { return __uint_as_float((unsigned)v << 16); }
; __device__ __forceinline__ unsigned f2bf(float f) { unsigned u = __float_as_uint(f); return (u + 0x7fffu + ((u >> 16) & 1u)) >> 16; }
; __device__ __forceinline__ unsigned pk2(float lo, float hi) { f32x2_t v = {lo, hi}; bf16x2_t b = __builtin_convertvector(v, bf16x2_t); return __builtin_bit_cast(unsigned, b); }
; __global__ void __launch_bounds__(512, 2) fwd_kernel(Args a) {
;     ...
;                     { const float x1 = bf2f(ra1), x2 = bf2f(ra2);
;                       z[basea + ia] = (bf16_t)f2bf(x1 * csa[0] - x2 * csa[1]); z[basea + 4 + ia] = (bf16_t)f2bf(x1 * csa[1] + x2 * csa[0]); }
;                     { const float v0 = __uint_as_float(wq.x << 16), v1 = __uint_as_float(wq.x & 0xffff0000u), v2 = __uint_as_float(wq.y << 16), v3 = __uint_as_float(wq.y & 0xffff0000u);
;                       const float rstd = rsqrtf(wave_sum((v0 * v0 + v1 * v1) + (v2 * v2 + v3 * v3)) * (1.0f / 256.0f) + EPS);
;                       u32x2 o; o.x = pk2(v0 * rstd, v1 * rstd); o.y = pk2(v2 * rstd, v3 * rstd); *(u32x2*)(z + 768 + 4 * lane) = o; }
;                     { const float v0 = __uint_as_float(wkv << 16), v1 = __uint_as_float(wkv & 0xffff0000u);
;                       const float rstd = rsqrtf(wave_sum(v0 * v0 + v1 * v1) * (1.0f / 128.0f) + EPS);
;                       *(unsigned*)(z + 1024 + 2 * lane) = pk2(v0 * rstd, v1 * rstd); }
;                     if (lane < 16) { const float x1 = bf2f(rk1), x2 = bf2f(rk2);
;                         *(unsigned*)(KPE + (size_t)m * 32 + 2 * lane) = pk2(x1 * csk[0] - x2 * csk[1], x1 * csk[1] + x2 * csk[0]); }
.Lzp_loop:
	v_readlane_b32 s36, v252, 21
	v_readlane_b32 s38, v252, 23
	v_readlane_b32 s39, v252, 24
	s_and_b32 s0, s22, 0x1fff
	v_readlane_b32 s14, v252, 19
	v_lshl_add_u64 v[64:65], s[38:39], 0, v[4:5]
	v_add_co_u32_e32 v64, vcc, 0x19000000, v64
	v_lshl_add_u64 v[72:73], s[38:39], 0, v[10:11]
	v_lshl_add_u64 v[68:69], s[38:39], 0, v[8:9]
	v_addc_co_u32_e32 v65, vcc, 0, v65, vcc
	v_lshl_add_u64 v[66:67], s[38:39], 0, v[2:3]
	global_load_dwordx2 v[74:75], v[72:73], off
	global_load_dword v91, v[68:69], off
	global_load_ushort v89, v[64:65], off offset:2304
	global_load_ushort v90, v[64:65], off offset:2336
	v_add_co_u32_e32 v64, vcc, 0x19000000, v66
	v_readlane_b32 s15, v252, 20
	s_nop 0
	v_addc_co_u32_e32 v65, vcc, 0, v67, vcc
	global_load_ushort v88, v[64:65], off offset:2368
	global_load_ushort v87, v[64:65], off offset:2496
	global_load_ushort v86, v[64:65], off offset:2624
	global_load_ushort v85, v[64:65], off offset:2752
	global_load_ushort v84, v[64:65], off offset:2880
	global_load_ushort v83, v[64:65], off offset:3008
	global_load_ushort v82, v[64:65], off offset:3136
	global_load_ushort v81, v[64:65], off offset:3264
	v_lshl_or_b32 v64, s0, 5, v30
	global_load_dwordx2 v[76:77], v64, s[14:15]
	v_lshlrev_b32_e32 v64, 2, v29
	s_bfe_u32 s4, s22, 0x70006
	s_and_b32 s5, s22, 63
	v_lshl_or_b32 v65, s0, 7, v64
	v_lshl_add_u64 v[92:93], s[38:39], 0, v[12:13]
	global_load_dwordx2 v[70:71], v65, s[66:67]
	v_mov_b32_e32 v65, s5
	v_mov_b32_e32 v94, s4
	s_mov_b32 s0, 0x19000000
	v_cndmask_b32_e64 v65, v65, v94, s[6:7]
	v_add_co_u32_e32 v92, vcc, s0, v92
	v_lshl_or_b32 v64, v65, 7, v64
	s_nop 0
	v_addc_co_u32_e32 v93, vcc, 0, v93, vcc
	global_load_dwordx2 v[64:65], v64, s[66:67]
	s_nop 0
	global_load_ushort v94, v[92:93], off
	global_load_ushort v95, v[92:93], off offset:8
	v_readlane_b32 s37, v252, 22
	s_add_i32 s22, s22, s54
	v_lshl_add_u64 v[8:9], v[8:9], 0, s[70:71]
	v_lshl_add_u64 v[10:11], v[10:11], 0, s[70:71]
	v_lshl_add_u64 v[2:3], v[2:3], 0, s[70:71]
	v_lshl_add_u64 v[12:13], v[12:13], 0, s[70:71]
	v_lshl_add_u64 v[4:5], v[4:5], 0, s[70:71]
	s_waitcnt vmcnt(30)
.Lzp_CA:
	v_lshlrev_b32_e32 v44, 16, v44
	v_lshlrev_b32_e32 v45, 16, v45
	v_mul_f32_e32 v46, v27, v45
	v_fma_f32 v46, v26, v44, -v46
	v_mul_f32_e32 v26, v26, v45
	v_fmac_f32_e32 v26, v27, v44
	v_bfe_u32 v47, v46, 16, 1
	v_bfe_u32 v27, v26, 16, 1
	v_add3_u32 v46, v46, v47, s13
	v_add3_u32 v26, v26, v27, s13
	global_store_short_d16_hi v[42:43], v46, off
	global_store_short_d16_hi v[42:43], v26, off offset:8
	v_and_b32_e32 v27, 0xffff0000, v25
	v_and_b32_e32 v43, 0xffff0000, v24
	v_lshlrev_b32_e32 v26, 16, v25
	v_lshlrev_b32_e32 v42, 16, v24
	v_mov_b32_e32 v44, v43
	v_mov_b32_e32 v45, v27
	v_mov_b32_e32 v24, v42
	v_mov_b32_e32 v25, v26
	v_pk_mul_f32 v[44:45], v[44:45], v[44:45]
	v_lshlrev_b32_e32 v46, 16, v41
	v_pk_fma_f32 v[24:25], v[24:25], v[24:25], v[44:45]
	v_and_b32_e32 v47, 0xffff0000, v41
	v_add_f32_e32 v24, v24, v25
	s_nop 1
	v_mov_b32_dpp v25, v24 quad_perm:[1,0,3,2] row_mask:0xf bank_mask:0xf
	v_pk_mul_f32 v[48:49], v[46:47], v[46:47]
	s_waitcnt lgkmcnt(0)
	v_add_f32_e32 v24, v24, v25
	s_nop 1
	v_mov_b32_dpp v25, v24 quad_perm:[2,3,0,1] row_mask:0xf bank_mask:0xf
	s_waitcnt lgkmcnt(0)
	v_add_f32_e32 v24, v24, v25
	s_nop 1
	v_mov_b32_dpp v25, v24 row_half_mirror row_mask:0xf bank_mask:0xf
	s_waitcnt lgkmcnt(0)
	v_add_f32_e32 v24, v24, v25
	s_nop 1
	v_mov_b32_dpp v25, v24 row_mirror row_mask:0xf bank_mask:0xf
	s_waitcnt lgkmcnt(0)
	v_add_f32_e32 v24, v24, v25
	ds_swizzle_b32 v25, v24 offset:swizzle(SWAP,16)
	s_waitcnt lgkmcnt(0)
	v_add_f32_e32 v25, v24, v25
	v_add_f32_e32 v24, v48, v49
	s_nop 1
	v_mov_b32_dpp v41, v24 quad_perm:[1,0,3,2] row_mask:0xf bank_mask:0xf
	v_mov_b32_e32 v45, v25
	s_nop 1
	v_permlane32_swap_b32_e32 v25, v45
	s_waitcnt lgkmcnt(0)
	v_add_f32_e32 v24, v24, v41
	s_nop 1
	v_mov_b32_dpp v41, v24 quad_perm:[2,3,0,1] row_mask:0xf bank_mask:0xf
	s_waitcnt lgkmcnt(0)
	v_add_f32_e32 v24, v24, v41
	s_nop 1
	v_mov_b32_dpp v41, v24 row_half_mirror row_mask:0xf bank_mask:0xf
	s_waitcnt lgkmcnt(0)
	v_add_f32_e32 v24, v24, v41
	s_nop 1
	v_mov_b32_dpp v41, v24 row_mirror row_mask:0xf bank_mask:0xf
	s_waitcnt lgkmcnt(0)
	v_add_f32_e32 v24, v24, v41
	ds_swizzle_b32 v41, v24 offset:swizzle(SWAP,16)
	s_waitcnt lgkmcnt(0)
	v_add_f32_e32 v24, v24, v41
	v_mov_b32_e32 v44, v24
	s_nop 1
	v_permlane32_swap_b32_e32 v24, v44
	v_pk_add_f32 v[24:25], v[24:25], v[44:45]
	s_nop 0
	v_pk_fma_f32 v[24:25], v[24:25], s[16:17], v[200:201] op_sel_hi:[1,1,0]
	s_nop 0
	v_mul_f32_e32 v41, 0x4b800000, v25
	v_cmp_gt_f32_e64 s[14:15], s44, v25
	v_cmp_gt_f32_e32 vcc, s44, v24
	s_nop 0
	v_cndmask_b32_e64 v25, v25, v41, s[14:15]
	v_rsq_f32_e32 v25, v25
	s_nop 0
	v_mul_f32_e32 v41, 0x45800000, v25
	v_cndmask_b32_e64 v44, v25, v41, s[14:15]
	v_pk_mul_f32 v[42:43], v[44:45], v[42:43] op_sel_hi:[0,1]
	v_pk_mul_f32 v[26:27], v[44:45], v[26:27] op_sel_hi:[0,1]
	v_cvt_pk_bf16_f32 v42, v42, v43
	v_cvt_pk_bf16_f32 v43, v26, v27
	global_store_dwordx2 v[22:23], v[42:43], off
	v_mul_f32_e32 v22, 0x4b800000, v24
	v_cndmask_b32_e32 v22, v24, v22, vcc
	v_rsq_f32_e32 v22, v22
	s_nop 0
	v_mul_f32_e32 v23, 0x45800000, v22
	v_cndmask_b32_e32 v22, v22, v23, vcc
	v_pk_mul_f32 v[22:23], v[22:23], v[46:47] op_sel_hi:[0,1]
	v_cvt_pk_bf16_f32 v22, v22, v23
	global_store_dword v[18:19], v22, off
	s_and_saveexec_b64 s[4:5], s[8:9]
	s_cbranch_execz .Lzp_x_ca
	v_lshlrev_b32_e32 v22, 16, v40
	v_lshlrev_b32_e32 v18, 16, v39
	v_pk_mul_f32 v[22:23], v[20:21], v[22:23] op_sel:[1,0] op_sel_hi:[0,0]
	v_readlane_b32 s36, v252, 21
	v_pk_fma_f32 v[24:25], v[20:21], v[18:19], v[22:23] neg_lo:[0,0,1] neg_hi:[0,0,1]
	v_pk_fma_f32 v[18:19], v[20:21], v[18:19], v[22:23] op_sel_hi:[1,0,1]
	v_readlane_b32 s38, v252, 23
	v_readlane_b32 s39, v252, 24
	v_cvt_pk_bf16_f32 v20, v24, v19
	v_readlane_b32 s37, v252, 22
	v_lshl_add_u64 v[18:19], s[38:39], 0, v[6:7]
	global_store_dword v[18:19], v20, off
; __device__ __forceinline__ float bf2f(bf16_t v) { return __uint_as_float((unsigned)v << 16); }
; __device__ __forceinline__ unsigned f2bf(float f) { unsigned u = __float_as_uint(f); return (u + 0x7fffu + ((u >> 16) & 1u)) >> 16; }
; #define SWZ_XOR(v, X) __int_as_float(__builtin_amdgcn_ds_swizzle(__float_as_int(v), ((X) << 10) | 0x1f))
; __device__ __forceinline__ float wave_sum(float v) {
;     v += SWZ_XOR(v, 1); v += SWZ_XOR(v, 2); v += SWZ_XOR(v, 4); v += SWZ_XOR(v, 8); v += SWZ_XOR(v, 16);
;     auto rr = __builtin_amdgcn_permlane32_swap(__float_as_uint(v), __float_as_uint(v), false, false); return __uint_as_float(rr[0]) + __uint_as_float(rr[1]);
; }
; __global__ void __launch_bounds__(512, 2) fwd_kernel(Args a) {
;     ...
; #pragma unroll
;                     for (int hd = 0; hd < 8; ++hd) { const int base = hd < 6 ? 1184 + hd * 64 : 1568 + (hd - 6) * 64; float v = bf2f(rh[hd]);
;                         const float rstd = rsqrtf(wave_sum(v * v) * (1.0f / 64.0f) + EPS); v = v * rstd * (hd < 6 ? gq : gk);
;                         const float p = SWZ_XOR(v, 16); const float ov = (lane & 16) ? (p * cs[1] + v * cs[0]) : (v * cs[0] - p * cs[1]);
;                         z[base + lane] = (bf16_t)f2bf(ov); }
.Lzp_x_ca:
	s_or_b64 exec, exec, s[4:5]
	v_lshlrev_b32_e32 v46, 16, v38
	v_lshlrev_b32_e32 v37, 16, v37
	v_mul_f32_e32 v18, v46, v46
	v_mul_f32_e32 v19, v37, v37
	s_nop 1
	v_mov_b32_dpp v18, v18 quad_perm:[1,0,3,2] row_mask:0xf bank_mask:0xf
	s_nop 1
	v_mov_b32_dpp v19, v19 quad_perm:[1,0,3,2] row_mask:0xf bank_mask:0xf
	s_mov_b32 s0, 0x358637bd
	v_lshlrev_b32_e32 v47, 16, v36
	v_lshlrev_b32_e32 v35, 16, v35
	s_waitcnt lgkmcnt(0)
	v_fmac_f32_e32 v18, v46, v46
	s_waitcnt lgkmcnt(0)
	v_fmac_f32_e32 v19, v37, v37
	s_nop 1
	v_mov_b32_dpp v20, v18 quad_perm:[2,3,0,1] row_mask:0xf bank_mask:0xf
	s_nop 1
	v_mov_b32_dpp v21, v19 quad_perm:[2,3,0,1] row_mask:0xf bank_mask:0xf
	v_mul_f32_e32 v49, v35, v35
	s_nop 1
	v_mov_b32_dpp v49, v49 quad_perm:[1,0,3,2] row_mask:0xf bank_mask:0xf
	s_mov_b64 s[4:5], 0x19000940
	s_waitcnt lgkmcnt(0)
	v_add_f32_e32 v18, v18, v20
	s_waitcnt lgkmcnt(0)
	v_add_f32_e32 v19, v19, v21
	s_nop 1
	v_mov_b32_dpp v20, v18 row_half_mirror row_mask:0xf bank_mask:0xf
	s_nop 1
	v_mov_b32_dpp v21, v19 row_half_mirror row_mask:0xf bank_mask:0xf
	s_waitcnt lgkmcnt(0)
	v_fmac_f32_e32 v49, v35, v35
	v_lshl_add_u64 v[26:27], v[16:17], 0, s[4:5]
	s_mov_b64 s[4:5], 0x190009c0
	s_waitcnt lgkmcnt(0)
	v_add_f32_e32 v18, v18, v20
	s_waitcnt lgkmcnt(0)
	v_add_f32_e32 v19, v19, v21
	s_nop 1
	v_mov_b32_dpp v20, v18 row_mirror row_mask:0xf bank_mask:0xf
	s_nop 1
	v_mov_b32_dpp v21, v19 row_mirror row_mask:0xf bank_mask:0xf
	v_lshl_add_u64 v[38:39], v[16:17], 0, s[4:5]
	v_lshlrev_b32_e32 v33, 16, v33
	s_mov_b64 s[4:5], 0x19000a40
	s_waitcnt lgkmcnt(0)
	v_add_f32_e32 v18, v18, v20
	s_waitcnt lgkmcnt(0)
	v_add_f32_e32 v22, v19, v21
	ds_swizzle_b32 v19, v18 offset:swizzle(SWAP,16)
	ds_swizzle_b32 v23, v22 offset:swizzle(SWAP,16)
	v_mov_b64_e32 v[20:21], s[0:1]
	v_lshl_add_u64 v[42:43], v[16:17], 0, s[4:5]
	s_mov_b64 s[4:5], 0x19000ac0
	s_waitcnt lgkmcnt(0)
	v_add_f32_e32 v19, v18, v19
	s_waitcnt lgkmcnt(0)
	v_add_f32_e32 v18, v22, v23
	v_mov_b32_e32 v23, v19
	v_mov_b32_e32 v22, v18
	s_nop 0
	v_permlane32_swap_b32_e32 v19, v23
	v_permlane32_swap_b32_e32 v18, v22
	v_pk_add_f32 v[18:19], v[18:19], v[22:23]
	v_lshl_add_u64 v[44:45], v[16:17], 0, s[4:5]
	v_pk_fma_f32 v[40:41], v[18:19], s[18:19], v[20:21] op_sel_hi:[1,0,0]
	v_lshlrev_b32_e32 v32, 16, v32
	v_mul_f32_e32 v18, 0x4b800000, v41
	v_cmp_gt_f32_e32 vcc, s44, v41
	v_mul_f32_e32 v48, 0x4b800000, v40
	v_lshlrev_b32_e32 v31, 16, v31
	v_cndmask_b32_e32 v18, v41, v18, vcc
	v_rsq_f32_e32 v18, v18
	s_mov_b64 s[4:5], 0x19000b40
	v_lshl_add_u64 v[24:25], v[16:17], 0, s[4:5]
	s_mov_b64 s[4:5], 0x19000bc0
	v_mul_f32_e32 v19, 0x45800000, v18
	v_cndmask_b32_e32 v18, v18, v19, vcc
	v_mul_f32_e32 v18, v18, v46
	v_mul_f32_e32 v41, v0, v18
	ds_swizzle_b32 v46, v41 offset:swizzle(SWAP,16)
	v_cmp_gt_f32_e32 vcc, s44, v40
	v_lshl_add_u64 v[22:23], v[16:17], 0, s[4:5]
	s_mov_b64 s[4:5], 0x19000c40
	v_cndmask_b32_e32 v40, v40, v48, vcc
	s_waitcnt lgkmcnt(0)
	v_mul_f32_e32 v36, v15, v46
	v_mul_f32_e32 v46, v47, v47
	s_nop 1
	v_mov_b32_dpp v46, v46 quad_perm:[1,0,3,2] row_mask:0xf bank_mask:0xf
	s_nop 1
	v_mov_b32_dpp v48, v49 quad_perm:[2,3,0,1] row_mask:0xf bank_mask:0xf
	v_cndmask_b32_e64 v36, v36, -v36, s[10:11]
	v_fmac_f32_e32 v36, v14, v41
	v_bfe_u32 v41, v36, 16, 1
	s_waitcnt lgkmcnt(0)
	v_fmac_f32_e32 v46, v47, v47
	s_nop 1
	v_mov_b32_dpp v50, v46 quad_perm:[2,3,0,1] row_mask:0xf bank_mask:0xf
	v_rsq_f32_e32 v40, v40
	v_add3_u32 v51, v36, v41, s13
	s_waitcnt lgkmcnt(0)
	v_add_f32_e32 v41, v49, v48
	s_nop 1
	v_mov_b32_dpp v48, v41 row_half_mirror row_mask:0xf bank_mask:0xf
	s_waitcnt lgkmcnt(0)
	v_add_f32_e32 v46, v46, v50
	s_nop 1
	v_mov_b32_dpp v50, v46 row_half_mirror row_mask:0xf bank_mask:0xf
	v_mul_f32_e32 v36, 0x45800000, v40
	v_cndmask_b32_e32 v36, v40, v36, vcc
	v_mul_f32_e32 v36, v36, v37
	s_waitcnt lgkmcnt(0)
	v_add_f32_e32 v37, v41, v48
	s_waitcnt lgkmcnt(0)
	v_add_f32_e32 v46, v46, v50
	s_nop 1
	v_mov_b32_dpp v49, v46 row_mirror row_mask:0xf bank_mask:0xf
	s_nop 1
	v_mov_b32_dpp v40, v37 row_mirror row_mask:0xf bank_mask:0xf
	v_mul_f32_e32 v48, v0, v36
	global_store_short_d16_hi v[26:27], v51, off
	v_lshl_add_u64 v[18:19], v[16:17], 0, s[4:5]
	s_waitcnt lgkmcnt(0)
	v_add_f32_e32 v41, v46, v49
	s_waitcnt lgkmcnt(0)
	v_add_f32_e32 v36, v37, v40
	ds_swizzle_b32 v46, v41 offset:swizzle(SWAP,16)
	ds_swizzle_b32 v40, v36 offset:swizzle(SWAP,16)
	ds_swizzle_b32 v49, v48 offset:swizzle(SWAP,16)
	s_mov_b64 s[4:5], 0x19000cc0
	s_waitcnt lgkmcnt(0)
	v_add_f32_e32 v37, v41, v46
	s_waitcnt lgkmcnt(0)
	v_add_f32_e32 v36, v36, v40
	v_mov_b32_e32 v41, v37
	v_mov_b32_e32 v40, v36
	s_nop 0
	v_permlane32_swap_b32_e32 v37, v41
	v_permlane32_swap_b32_e32 v36, v40
	v_pk_add_f32 v[36:37], v[36:37], v[40:41]
	s_waitcnt lgkmcnt(0)
	v_mul_f32_e32 v26, v15, v49
	v_pk_fma_f32 v[36:37], v[36:37], s[18:19], v[20:21] op_sel_hi:[1,0,0]
	v_cndmask_b32_e64 v26, v26, -v26, s[10:11]
	v_mul_f32_e32 v40, 0x4b800000, v37
	v_cmp_gt_f32_e32 vcc, s44, v37
	v_fmac_f32_e32 v26, v14, v48
	v_lshl_add_u64 v[16:17], v[16:17], 0, s[4:5]
	v_cndmask_b32_e32 v37, v37, v40, vcc
	v_rsq_f32_e32 v37, v37
	v_bfe_u32 v40, v26, 16, 1
	v_add3_u32 v26, v26, v40, s13
	global_store_short_d16_hi v[38:39], v26, off
	v_mul_f32_e32 v27, 0x45800000, v37
	v_cndmask_b32_e32 v27, v37, v27, vcc
	v_mul_f32_e32 v27, v27, v47
	v_mul_f32_e32 v27, v0, v27
	ds_swizzle_b32 v37, v27 offset:swizzle(SWAP,16)
	v_mul_f32_e32 v39, v33, v33
	s_nop 1
	v_mov_b32_dpp v39, v39 quad_perm:[1,0,3,2] row_mask:0xf bank_mask:0xf
	v_mul_f32_e32 v38, 0x4b800000, v36
	v_cmp_gt_f32_e32 vcc, s44, v36
	s_waitcnt lgkmcnt(0)
; __device__ __forceinline__ float bf2f(bf16_t v) { return __uint_as_float((unsigned)v << 16); }
; __device__ __forceinline__ unsigned f2bf(float f) { unsigned u = __float_as_uint(f); return (u + 0x7fffu + ((u >> 16) & 1u)) >> 16; }
; #define SWZ_XOR(v, X) __int_as_float(__builtin_amdgcn_ds_swizzle(__float_as_int(v), ((X) << 10) | 0x1f))
; __global__ void __launch_bounds__(512, 2) fwd_kernel(Args a) {
;     ...
; #pragma unroll
;                     for (int hd = 0; hd < 8; ++hd) { const int base = hd < 6 ? 1184 + hd * 64 : 1568 + (hd - 6) * 64; float v = bf2f(rh[hd]);
;                         const float rstd = rsqrtf(wave_sum(v * v) * (1.0f / 64.0f) + EPS); v = v * rstd * (hd < 6 ? gq : gk);
;                         const float p = SWZ_XOR(v, 16); const float ov = (lane & 16) ? (p * cs[1] + v * cs[0]) : (v * cs[0] - p * cs[1]);
;                         z[base + lane] = (bf16_t)f2bf(ov); }
	v_mul_f32_e32 v26, v15, v37
	v_lshlrev_b32_e32 v37, 16, v34
	v_mul_f32_e32 v34, v37, v37
	s_nop 1
	v_mov_b32_dpp v34, v34 quad_perm:[1,0,3,2] row_mask:0xf bank_mask:0xf
	s_waitcnt lgkmcnt(0)
	v_fmac_f32_e32 v39, v33, v33
	v_cndmask_b32_e32 v36, v36, v38, vcc
	s_nop 1
	v_mov_b32_dpp v38, v39 quad_perm:[2,3,0,1] row_mask:0xf bank_mask:0xf
	v_cndmask_b32_e64 v26, v26, -v26, s[10:11]
	s_waitcnt lgkmcnt(0)
	v_fmac_f32_e32 v34, v37, v37
	s_nop 1
	v_mov_b32_dpp v40, v34 quad_perm:[2,3,0,1] row_mask:0xf bank_mask:0xf
	v_fmac_f32_e32 v26, v14, v27
	v_bfe_u32 v27, v26, 16, 1
	v_add3_u32 v41, v26, v27, s13
	s_waitcnt lgkmcnt(0)
	v_add_f32_e32 v27, v39, v38
	s_waitcnt lgkmcnt(0)
	v_add_f32_e32 v34, v34, v40
	v_rsq_f32_e32 v36, v36
	s_nop 1
	v_mov_b32_dpp v40, v34 row_half_mirror row_mask:0xf bank_mask:0xf
	s_nop 1
	v_mov_b32_dpp v38, v27 row_half_mirror row_mask:0xf bank_mask:0xf
	v_lshl_add_u64 v[6:7], v[6:7], 0, s[76:77]
	v_mul_f32_e32 v26, 0x45800000, v36
	v_cndmask_b32_e32 v26, v36, v26, vcc
	s_waitcnt lgkmcnt(0)
	v_add_f32_e32 v34, v34, v40
	s_waitcnt lgkmcnt(0)
	v_add_f32_e32 v27, v27, v38
	s_nop 1
	v_mov_b32_dpp v39, v34 row_mirror row_mask:0xf bank_mask:0xf
	v_mul_f32_e32 v26, v26, v35
	s_nop 1
	v_mov_b32_dpp v35, v27 row_mirror row_mask:0xf bank_mask:0xf
	v_mul_f32_e32 v38, v0, v26
	s_waitcnt lgkmcnt(0)
	v_add_f32_e32 v34, v34, v39
	ds_swizzle_b32 v36, v34 offset:swizzle(SWAP,16)
	s_waitcnt lgkmcnt(0)
	v_add_f32_e32 v26, v27, v35
	ds_swizzle_b32 v40, v26 offset:swizzle(SWAP,16)
	ds_swizzle_b32 v39, v38 offset:swizzle(SWAP,16)
	s_waitcnt lgkmcnt(0)
	v_add_f32_e32 v27, v34, v36
	v_mov_b32_e32 v35, v27
	s_waitcnt lgkmcnt(0)
	v_add_f32_e32 v26, v26, v40
	v_mov_b32_e32 v34, v26
	v_permlane32_swap_b32_e32 v27, v35
	s_nop 0
	v_permlane32_swap_b32_e32 v26, v34
	v_pk_add_f32 v[26:27], v[26:27], v[34:35]
	v_pk_fma_f32 v[26:27], v[26:27], s[18:19], v[20:21] op_sel_hi:[1,0,0]
	v_mul_f32_e32 v34, 0x4b800000, v27
	v_cmp_gt_f32_e32 vcc, s44, v27
	v_cndmask_b32_e32 v27, v27, v34, vcc
	v_rsq_f32_e32 v27, v27
	s_waitcnt lgkmcnt(0)
	v_mul_f32_e32 v34, v15, v39
	v_cndmask_b32_e64 v34, v34, -v34, s[10:11]
	v_fmac_f32_e32 v34, v14, v38
	v_mul_f32_e32 v35, 0x45800000, v27
	v_cndmask_b32_e32 v27, v27, v35, vcc
	v_mul_f32_e32 v27, v27, v37
	v_mul_f32_e32 v27, v0, v27
	ds_swizzle_b32 v35, v27 offset:swizzle(SWAP,16)
	v_bfe_u32 v36, v34, 16, 1
	v_add3_u32 v34, v34, v36, s13
	global_store_short_d16_hi v[44:45], v34, off
	v_cmp_gt_f32_e32 vcc, s44, v26
	s_waitcnt lgkmcnt(0)
	v_mul_f32_e32 v34, v15, v35
	v_cndmask_b32_e64 v34, v34, -v34, s[10:11]
	v_fmac_f32_e32 v34, v14, v27
	v_bfe_u32 v27, v34, 16, 1
	v_add3_u32 v27, v34, v27, s13
	v_mul_f32_e32 v34, 0x4b800000, v26
	v_cndmask_b32_e32 v26, v26, v34, vcc
	v_mul_f32_e32 v34, v32, v32
	s_nop 1
	v_mov_b32_dpp v34, v34 quad_perm:[1,0,3,2] row_mask:0xf bank_mask:0xf
	v_mul_f32_e32 v35, v31, v31
	s_nop 1
	v_mov_b32_dpp v35, v35 quad_perm:[1,0,3,2] row_mask:0xf bank_mask:0xf
	global_store_short_d16_hi v[24:25], v27, off
	v_rsq_f32_e32 v26, v26
	s_waitcnt lgkmcnt(0)
	v_fmac_f32_e32 v34, v32, v32
	s_nop 1
	v_mov_b32_dpp v36, v34 quad_perm:[2,3,0,1] row_mask:0xf bank_mask:0xf
	s_waitcnt lgkmcnt(0)
	v_fmac_f32_e32 v35, v31, v31
	s_nop 1
	v_mov_b32_dpp v25, v35 quad_perm:[2,3,0,1] row_mask:0xf bank_mask:0xf
	v_mul_f32_e32 v24, 0x45800000, v26
	v_cndmask_b32_e32 v24, v26, v24, vcc
	s_waitcnt lgkmcnt(0)
	v_add_f32_e32 v27, v34, v36
	s_nop 1
	v_mov_b32_dpp v34, v27 row_half_mirror row_mask:0xf bank_mask:0xf
	s_waitcnt lgkmcnt(0)
	v_add_f32_e32 v25, v35, v25
	s_nop 1
	v_mov_b32_dpp v26, v25 row_half_mirror row_mask:0xf bank_mask:0xf
	v_mul_f32_e32 v24, v24, v33
	global_store_short_d16_hi v[42:43], v41, off
	s_waitcnt lgkmcnt(0)
	v_add_f32_e32 v27, v27, v34
	v_mul_f32_e32 v34, v0, v24
	ds_swizzle_b32 v24, v34 offset:swizzle(SWAP,16)
	s_waitcnt lgkmcnt(0)
	v_add_f32_e32 v25, v25, v26
	s_nop 1
	v_mov_b32_dpp v33, v27 row_mirror row_mask:0xf bank_mask:0xf
	s_nop 1
	v_mov_b32_dpp v26, v25 row_mirror row_mask:0xf bank_mask:0xf
	s_waitcnt lgkmcnt(0)
	v_mul_f32_e32 v24, v15, v24
	v_cndmask_b32_e64 v35, v24, -v24, s[10:11]
	s_waitcnt lgkmcnt(0)
	v_add_f32_e32 v27, v27, v33
	s_waitcnt lgkmcnt(0)
	v_add_f32_e32 v24, v25, v26
	ds_swizzle_b32 v33, v27 offset:swizzle(SWAP,16)
	ds_swizzle_b32 v26, v24 offset:swizzle(SWAP,16)
	v_fmac_f32_e32 v35, v14, v34
	s_waitcnt lgkmcnt(0)
	v_add_f32_e32 v25, v27, v33
	s_waitcnt lgkmcnt(0)
	v_add_f32_e32 v24, v24, v26
	v_mov_b32_e32 v27, v25
	v_mov_b32_e32 v26, v24
	s_nop 0
	v_permlane32_swap_b32_e32 v25, v27
	v_permlane32_swap_b32_e32 v24, v26
	v_pk_add_f32 v[24:25], v[24:25], v[26:27]
	s_nop 0
	v_pk_fma_f32 v[20:21], v[24:25], s[18:19], v[20:21] op_sel_hi:[1,0,0]
	s_nop 0
	v_mul_f32_e32 v24, 0x4b800000, v21
	v_cmp_gt_f32_e32 vcc, s44, v21
	v_mul_f32_e32 v26, 0x4b800000, v20
	s_nop 0
	v_cndmask_b32_e32 v21, v21, v24, vcc
	v_rsq_f32_e32 v21, v21
	v_bfe_u32 v24, v35, 16, 1
	v_add3_u32 v24, v35, v24, s13
	global_store_short_d16_hi v[22:23], v24, off
	v_mul_f32_e32 v25, 0x45800000, v21
	v_cndmask_b32_e32 v21, v21, v25, vcc
	v_cmp_gt_f32_e32 vcc, s44, v20
	v_mul_f32_e32 v21, v21, v32
	v_mul_f32_e32 v21, v28, v21
	v_cndmask_b32_e32 v20, v20, v26, vcc
	v_rsq_f32_e32 v20, v20
	ds_swizzle_b32 v25, v21 offset:swizzle(SWAP,16)
	v_mul_f32_e32 v23, 0x45800000, v20
	v_cndmask_b32_e32 v20, v20, v23, vcc
	v_mul_f32_e32 v20, v20, v31
	v_mul_f32_e32 v20, v28, v20
	ds_swizzle_b32 v23, v20 offset:swizzle(SWAP,16)
	s_waitcnt lgkmcnt(0)
	v_mul_f32_e32 v22, v15, v25
	v_cndmask_b32_e64 v22, v22, -v22, s[10:11]
	v_fmac_f32_e32 v22, v14, v21
	v_bfe_u32 v21, v22, 16, 1
	s_waitcnt lgkmcnt(0)
	v_mul_f32_e32 v15, v15, v23
	v_cndmask_b32_e64 v15, v15, -v15, s[10:11]
	v_fmac_f32_e32 v15, v14, v20
	v_bfe_u32 v14, v15, 16, 1
	v_add3_u32 v21, v22, v21, s13
	v_add3_u32 v14, v15, v14, s13
	global_store_short_d16_hi v[18:19], v21, off
	global_store_short_d16_hi v[16:17], v14, off
	s_sub_i32 s100, s100, 1
	s_cmp_eq_u32 s100, 0
	s_cbranch_scc1 .Lzp_last
; __global__ void __launch_bounds__(512, 2) fwd_kernel(Args a) {
;     ...
;                 for (int m = gw; m < MTOK; m += NGW) {
;                     bf16_t* z = Z + (size_t)m * ZC; const int pos = m & (SEQ - 1), rowp = pos >> 6, colp = pos & 63;
;                     const int grp = lane >> 2, ia = lane & 3, basea = (grp < 8 ? 0 : 256) + (grp & 7) * 32;
;                     const bf16_t ra1 = z[basea + ia], ra2 = z[basea + 4 + ia];
;                     const u32x2 wq = *(const u32x2*)(z + 768 + 4 * lane);
;                     const unsigned wkv = *(const unsigned*)(z + 1024 + 2 * lane);
;                     const bf16_t rk1 = z[1152 + (lane & 15)], rk2 = z[1168 + (lane & 15)];
;                     bf16_t rh[8];
; #pragma unroll
;                     for (int hd = 0; hd < 8; ++hd) rh[hd] = z[(hd < 6 ? 1184 + hd * 64 : 1568 + (hd - 6) * 64) + lane];
;                     const f32x2_t csa = *(const f32x2_t*)(taba + (size_t)(pos * 4 + ia) * 2);
;                     const f32x2_t csk = *(const f32x2_t*)(tab32 + (size_t)(pos * 16 + (lane & 15)) * 2);
;                     const int pp = lane < 32 ? rowp : colp; const f32x2_t cs = *(const f32x2_t*)(tab32 + (size_t)(pp * 16 + (lane & 15)) * 2);
;                     asm volatile("" ::: "memory");
;                     { const float x1 = bf2f(ra1), x2 = bf2f(ra2);
;                       z[basea + ia] = (bf16_t)f2bf(x1 * csa[0] - x2 * csa[1]); z[basea + 4 + ia] = (bf16_t)f2bf(x1 * csa[1] + x2 * csa[0]); }
;                     { const float v0 = __uint_as_float(wq.x << 16), v1 = __uint_as_float(wq.x & 0xffff0000u), v2 = __uint_as_float(wq.y << 16), v3 = __uint_as_float(wq.y & 0xffff0000u);
;                       const float rstd = rsqrtf(wave_sum((v0 * v0 + v1 * v1) + (v2 * v2 + v3 * v3)) * (1.0f / 256.0f) + EPS);
;                       u32x2 o; o.x = pk2(v0 * rstd, v1 * rstd); o.y = pk2(v2 * rstd, v3 * rstd); *(u32x2*)(z + 768 + 4 * lane) = o; }
;                     { const float v0 = __uint_as_float(wkv << 16), v1 = __uint_as_float(wkv & 0xffff0000u);
;                       const float rstd = rsqrtf(wave_sum(v0 * v0 + v1 * v1) * (1.0f / 128.0f) + EPS);
;                       *(unsigned*)(z + 1024 + 2 * lane) = pk2(v0 * rstd, v1 * rstd); }
;                     if (lane < 16) { const float x1 = bf2f(rk1), x2 = bf2f(rk2);
	v_readlane_b32 s36, v252, 21
	v_readlane_b32 s38, v252, 23
	v_readlane_b32 s39, v252, 24
	s_and_b32 s0, s22, 0x1fff
	v_readlane_b32 s14, v252, 19
	v_lshl_add_u64 v[14:15], s[38:39], 0, v[4:5]
	v_add_co_u32_e32 v14, vcc, 0x19000000, v14
	v_lshl_add_u64 v[22:23], s[38:39], 0, v[10:11]
	v_lshl_add_u64 v[18:19], s[38:39], 0, v[8:9]
	v_addc_co_u32_e32 v15, vcc, 0, v15, vcc
	v_lshl_add_u64 v[16:17], s[38:39], 0, v[2:3]
	global_load_dwordx2 v[24:25], v[22:23], off
	global_load_dword v41, v[18:19], off
	global_load_ushort v39, v[14:15], off offset:2304
	global_load_ushort v40, v[14:15], off offset:2336
	v_add_co_u32_e32 v14, vcc, 0x19000000, v16
	v_readlane_b32 s15, v252, 20
	s_nop 0
	v_addc_co_u32_e32 v15, vcc, 0, v17, vcc
	global_load_ushort v38, v[14:15], off offset:2368
	global_load_ushort v37, v[14:15], off offset:2496
	global_load_ushort v36, v[14:15], off offset:2624
	global_load_ushort v35, v[14:15], off offset:2752
	global_load_ushort v34, v[14:15], off offset:2880
	global_load_ushort v33, v[14:15], off offset:3008
	global_load_ushort v32, v[14:15], off offset:3136
	global_load_ushort v31, v[14:15], off offset:3264
	v_lshl_or_b32 v14, s0, 5, v30
	global_load_dwordx2 v[26:27], v14, s[14:15]
	v_lshlrev_b32_e32 v14, 2, v29
	s_bfe_u32 s4, s22, 0x70006
	s_and_b32 s5, s22, 63
	v_lshl_or_b32 v15, s0, 7, v14
	v_lshl_add_u64 v[42:43], s[38:39], 0, v[12:13]
	global_load_dwordx2 v[20:21], v15, s[66:67]
	v_mov_b32_e32 v15, s5
	v_mov_b32_e32 v44, s4
	s_mov_b32 s0, 0x19000000
	v_cndmask_b32_e64 v15, v15, v44, s[6:7]
	v_add_co_u32_e32 v42, vcc, s0, v42
	v_lshl_or_b32 v14, v15, 7, v14
	s_nop 0
	v_addc_co_u32_e32 v43, vcc, 0, v43, vcc
	global_load_dwordx2 v[14:15], v14, s[66:67]
	s_nop 0
	global_load_ushort v44, v[42:43], off
	global_load_ushort v45, v[42:43], off offset:8
	v_readlane_b32 s37, v252, 22
	s_add_i32 s22, s22, s54
	v_lshl_add_u64 v[8:9], v[8:9], 0, s[70:71]
	v_lshl_add_u64 v[10:11], v[10:11], 0, s[70:71]
	v_lshl_add_u64 v[2:3], v[2:3], 0, s[70:71]
	v_lshl_add_u64 v[12:13], v[12:13], 0, s[70:71]
	v_lshl_add_u64 v[4:5], v[4:5], 0, s[70:71]
	s_waitcnt vmcnt(30)
	v_lshlrev_b32_e32 v94, 16, v94
	v_lshlrev_b32_e32 v95, 16, v95
	v_mul_f32_e32 v96, v77, v95
	v_fma_f32 v96, v76, v94, -v96
	v_mul_f32_e32 v76, v76, v95
	v_fmac_f32_e32 v76, v77, v94
	v_bfe_u32 v97, v96, 16, 1
	v_bfe_u32 v77, v76, 16, 1
	v_add3_u32 v96, v96, v97, s13
	v_add3_u32 v76, v76, v77, s13
	global_store_short_d16_hi v[92:93], v96, off
	global_store_short_d16_hi v[92:93], v76, off offset:8
	v_and_b32_e32 v77, 0xffff0000, v75
	v_and_b32_e32 v93, 0xffff0000, v74
	v_lshlrev_b32_e32 v76, 16, v75
	v_lshlrev_b32_e32 v92, 16, v74
	v_mov_b32_e32 v94, v93
	v_mov_b32_e32 v95, v77
	v_mov_b32_e32 v74, v92
	v_mov_b32_e32 v75, v76
	v_pk_mul_f32 v[94:95], v[94:95], v[94:95]
	v_lshlrev_b32_e32 v96, 16, v91
	v_pk_fma_f32 v[74:75], v[74:75], v[74:75], v[94:95]
	v_and_b32_e32 v97, 0xffff0000, v91
	v_add_f32_e32 v74, v74, v75
	s_nop 1
	v_mov_b32_dpp v75, v74 quad_perm:[1,0,3,2] row_mask:0xf bank_mask:0xf
	v_pk_mul_f32 v[98:99], v[96:97], v[96:97]
	s_waitcnt lgkmcnt(0)
	v_add_f32_e32 v74, v74, v75
	s_nop 1
	v_mov_b32_dpp v75, v74 quad_perm:[2,3,0,1] row_mask:0xf bank_mask:0xf
	s_waitcnt lgkmcnt(0)
	v_add_f32_e32 v74, v74, v75
	s_nop 1
	v_mov_b32_dpp v75, v74 row_half_mirror row_mask:0xf bank_mask:0xf
	s_waitcnt lgkmcnt(0)
	v_add_f32_e32 v74, v74, v75
	s_nop 1
	v_mov_b32_dpp v75, v74 row_mirror row_mask:0xf bank_mask:0xf
	s_waitcnt lgkmcnt(0)
	v_add_f32_e32 v74, v74, v75
	ds_swizzle_b32 v75, v74 offset:swizzle(SWAP,16)
	s_waitcnt lgkmcnt(0)
	v_add_f32_e32 v75, v74, v75
	v_add_f32_e32 v74, v98, v99
	s_nop 1
	v_mov_b32_dpp v91, v74 quad_perm:[1,0,3,2] row_mask:0xf bank_mask:0xf
	v_mov_b32_e32 v95, v75
	s_nop 1
	v_permlane32_swap_b32_e32 v75, v95
	s_waitcnt lgkmcnt(0)
	v_add_f32_e32 v74, v74, v91
	s_nop 1
	v_mov_b32_dpp v91, v74 quad_perm:[2,3,0,1] row_mask:0xf bank_mask:0xf
	s_waitcnt lgkmcnt(0)
	v_add_f32_e32 v74, v74, v91
	s_nop 1
	v_mov_b32_dpp v91, v74 row_half_mirror row_mask:0xf bank_mask:0xf
	s_waitcnt lgkmcnt(0)
	v_add_f32_e32 v74, v74, v91
	s_nop 1
	v_mov_b32_dpp v91, v74 row_mirror row_mask:0xf bank_mask:0xf
	s_waitcnt lgkmcnt(0)
	v_add_f32_e32 v74, v74, v91
	ds_swizzle_b32 v91, v74 offset:swizzle(SWAP,16)
	s_waitcnt lgkmcnt(0)
	v_add_f32_e32 v74, v74, v91
	v_mov_b32_e32 v94, v74
	s_nop 1
	v_permlane32_swap_b32_e32 v74, v94
	v_pk_add_f32 v[74:75], v[74:75], v[94:95]
	s_nop 0
	v_pk_fma_f32 v[74:75], v[74:75], s[16:17], v[200:201] op_sel_hi:[1,1,0]
	s_nop 0
	v_mul_f32_e32 v91, 0x4b800000, v75
	v_cmp_gt_f32_e64 s[14:15], s44, v75
	v_cmp_gt_f32_e32 vcc, s44, v74
	s_nop 0
	v_cndmask_b32_e64 v75, v75, v91, s[14:15]
	v_rsq_f32_e32 v75, v75
	s_nop 0
	v_mul_f32_e32 v91, 0x45800000, v75
	v_cndmask_b32_e64 v94, v75, v91, s[14:15]
	v_pk_mul_f32 v[92:93], v[94:95], v[92:93] op_sel_hi:[0,1]
	v_pk_mul_f32 v[76:77], v[94:95], v[76:77] op_sel_hi:[0,1]
	v_cvt_pk_bf16_f32 v92, v92, v93
	v_cvt_pk_bf16_f32 v93, v76, v77
	global_store_dwordx2 v[72:73], v[92:93], off
	v_mul_f32_e32 v72, 0x4b800000, v74
	v_cndmask_b32_e32 v72, v74, v72, vcc
	v_rsq_f32_e32 v72, v72
	s_nop 0
	v_mul_f32_e32 v73, 0x45800000, v72
	v_cndmask_b32_e32 v72, v72, v73, vcc
	v_pk_mul_f32 v[72:73], v[72:73], v[96:97] op_sel_hi:[0,1]
	v_cvt_pk_bf16_f32 v72, v72, v73
	global_store_dword v[68:69], v72, off
	s_and_saveexec_b64 s[4:5], s[8:9]
	s_cbranch_execz .Lzp_x_cb
	v_lshlrev_b32_e32 v72, 16, v90
	v_lshlrev_b32_e32 v68, 16, v89
	v_pk_mul_f32 v[72:73], v[70:71], v[72:73] op_sel:[1,0] op_sel_hi:[0,0]
	v_readlane_b32 s36, v252, 21
	v_pk_fma_f32 v[74:75], v[70:71], v[68:69], v[72:73] neg_lo:[0,0,1] neg_hi:[0,0,1]
	v_pk_fma_f32 v[68:69], v[70:71], v[68:69], v[72:73] op_sel_hi:[1,0,1]
	v_readlane_b32 s38, v252, 23
	v_readlane_b32 s39, v252, 24
	v_cvt_pk_bf16_f32 v70, v74, v69
	v_readlane_b32 s37, v252, 22
	v_lshl_add_u64 v[68:69], s[38:39], 0, v[6:7]
	global_store_dword v[68:69], v70, off
; __device__ __forceinline__ float bf2f(bf16_t v) { return __uint_as_float((unsigned)v << 16); }
; __device__ __forceinline__ unsigned f2bf(float f) { unsigned u = __float_as_uint(f); return (u + 0x7fffu + ((u >> 16) & 1u)) >> 16; }
; #define SWZ_XOR(v, X) __int_as_float(__builtin_amdgcn_ds_swizzle(__float_as_int(v), ((X) << 10) | 0x1f))
; __global__ void __launch_bounds__(512, 2) fwd_kernel(Args a) {
;     ...
; #pragma unroll
;                     for (int hd = 0; hd < 8; ++hd) { const int base = hd < 6 ? 1184 + hd * 64 : 1568 + (hd - 6) * 64; float v = bf2f(rh[hd]);
;                         const float rstd = rsqrtf(wave_sum(v * v) * (1.0f / 64.0f) + EPS); v = v * rstd * (hd < 6 ? gq : gk);
;                         const float p = SWZ_XOR(v, 16); const float ov = (lane & 16) ? (p * cs[1] + v * cs[0]) : (v * cs[0] - p * cs[1]);
;                         z[base + lane] = (bf16_t)f2bf(ov); }
.Lzp_x_cb:
	s_or_b64 exec, exec, s[4:5]
	v_lshlrev_b32_e32 v96, 16, v88
	v_lshlrev_b32_e32 v87, 16, v87
	v_mul_f32_e32 v68, v96, v96
	v_mul_f32_e32 v69, v87, v87
	s_nop 1
	v_mov_b32_dpp v68, v68 quad_perm:[1,0,3,2] row_mask:0xf bank_mask:0xf
	s_nop 1
	v_mov_b32_dpp v69, v69 quad_perm:[1,0,3,2] row_mask:0xf bank_mask:0xf
	s_mov_b32 s0, 0x358637bd
	v_lshlrev_b32_e32 v97, 16, v86
	v_lshlrev_b32_e32 v85, 16, v85
	s_waitcnt lgkmcnt(0)
	v_fmac_f32_e32 v68, v96, v96
	s_waitcnt lgkmcnt(0)
	v_fmac_f32_e32 v69, v87, v87
	s_nop 1
	v_mov_b32_dpp v70, v68 quad_perm:[2,3,0,1] row_mask:0xf bank_mask:0xf
	s_nop 1
	v_mov_b32_dpp v71, v69 quad_perm:[2,3,0,1] row_mask:0xf bank_mask:0xf
	v_mul_f32_e32 v99, v85, v85
	s_nop 1
	v_mov_b32_dpp v99, v99 quad_perm:[1,0,3,2] row_mask:0xf bank_mask:0xf
	s_mov_b64 s[4:5], 0x19000940
	s_waitcnt lgkmcnt(0)
	v_add_f32_e32 v68, v68, v70
	s_waitcnt lgkmcnt(0)
	v_add_f32_e32 v69, v69, v71
	s_nop 1
	v_mov_b32_dpp v70, v68 row_half_mirror row_mask:0xf bank_mask:0xf
	s_nop 1
	v_mov_b32_dpp v71, v69 row_half_mirror row_mask:0xf bank_mask:0xf
	s_waitcnt lgkmcnt(0)
	v_fmac_f32_e32 v99, v85, v85
	v_lshl_add_u64 v[76:77], v[66:67], 0, s[4:5]
	s_mov_b64 s[4:5], 0x190009c0
	s_waitcnt lgkmcnt(0)
	v_add_f32_e32 v68, v68, v70
	s_waitcnt lgkmcnt(0)
	v_add_f32_e32 v69, v69, v71
	s_nop 1
	v_mov_b32_dpp v70, v68 row_mirror row_mask:0xf bank_mask:0xf
	s_nop 1
	v_mov_b32_dpp v71, v69 row_mirror row_mask:0xf bank_mask:0xf
	v_lshl_add_u64 v[88:89], v[66:67], 0, s[4:5]
	v_lshlrev_b32_e32 v83, 16, v83
	s_mov_b64 s[4:5], 0x19000a40
	s_waitcnt lgkmcnt(0)
	v_add_f32_e32 v68, v68, v70
	s_waitcnt lgkmcnt(0)
	v_add_f32_e32 v72, v69, v71
	ds_swizzle_b32 v69, v68 offset:swizzle(SWAP,16)
	ds_swizzle_b32 v73, v72 offset:swizzle(SWAP,16)
	v_mov_b64_e32 v[70:71], s[0:1]
	v_lshl_add_u64 v[92:93], v[66:67], 0, s[4:5]
	s_mov_b64 s[4:5], 0x19000ac0
	s_waitcnt lgkmcnt(0)
	v_add_f32_e32 v69, v68, v69
	s_waitcnt lgkmcnt(0)
	v_add_f32_e32 v68, v72, v73
	v_mov_b32_e32 v73, v69
	v_mov_b32_e32 v72, v68
	s_nop 0
	v_permlane32_swap_b32_e32 v69, v73
	v_permlane32_swap_b32_e32 v68, v72
	v_pk_add_f32 v[68:69], v[68:69], v[72:73]
	v_lshl_add_u64 v[94:95], v[66:67], 0, s[4:5]
	v_pk_fma_f32 v[90:91], v[68:69], s[18:19], v[70:71] op_sel_hi:[1,0,0]
	v_lshlrev_b32_e32 v82, 16, v82
	v_mul_f32_e32 v68, 0x4b800000, v91
	v_cmp_gt_f32_e32 vcc, s44, v91
	v_mul_f32_e32 v98, 0x4b800000, v90
	v_lshlrev_b32_e32 v81, 16, v81
	v_cndmask_b32_e32 v68, v91, v68, vcc
	v_rsq_f32_e32 v68, v68
	s_mov_b64 s[4:5], 0x19000b40
	v_lshl_add_u64 v[74:75], v[66:67], 0, s[4:5]
	s_mov_b64 s[4:5], 0x19000bc0
	v_mul_f32_e32 v69, 0x45800000, v68
	v_cndmask_b32_e32 v68, v68, v69, vcc
	v_mul_f32_e32 v68, v68, v96
	v_mul_f32_e32 v91, v0, v68
	ds_swizzle_b32 v96, v91 offset:swizzle(SWAP,16)
	v_cmp_gt_f32_e32 vcc, s44, v90
	v_lshl_add_u64 v[72:73], v[66:67], 0, s[4:5]
	s_mov_b64 s[4:5], 0x19000c40
	v_cndmask_b32_e32 v90, v90, v98, vcc
	s_waitcnt lgkmcnt(0)
	v_mul_f32_e32 v86, v65, v96
	v_mul_f32_e32 v96, v97, v97
	s_nop 1
	v_mov_b32_dpp v96, v96 quad_perm:[1,0,3,2] row_mask:0xf bank_mask:0xf
	s_nop 1
	v_mov_b32_dpp v98, v99 quad_perm:[2,3,0,1] row_mask:0xf bank_mask:0xf
	v_cndmask_b32_e64 v86, v86, -v86, s[10:11]
	v_fmac_f32_e32 v86, v64, v91
	v_bfe_u32 v91, v86, 16, 1
	s_waitcnt lgkmcnt(0)
	v_fmac_f32_e32 v96, v97, v97
	s_nop 1
	v_mov_b32_dpp v100, v96 quad_perm:[2,3,0,1] row_mask:0xf bank_mask:0xf
	v_rsq_f32_e32 v90, v90
	v_add3_u32 v101, v86, v91, s13
	s_waitcnt lgkmcnt(0)
	v_add_f32_e32 v91, v99, v98
	s_nop 1
	v_mov_b32_dpp v98, v91 row_half_mirror row_mask:0xf bank_mask:0xf
	s_waitcnt lgkmcnt(0)
	v_add_f32_e32 v96, v96, v100
	s_nop 1
	v_mov_b32_dpp v100, v96 row_half_mirror row_mask:0xf bank_mask:0xf
	v_mul_f32_e32 v86, 0x45800000, v90
	v_cndmask_b32_e32 v86, v90, v86, vcc
	v_mul_f32_e32 v86, v86, v87
	s_waitcnt lgkmcnt(0)
	v_add_f32_e32 v87, v91, v98
	s_waitcnt lgkmcnt(0)
	v_add_f32_e32 v96, v96, v100
	s_nop 1
	v_mov_b32_dpp v99, v96 row_mirror row_mask:0xf bank_mask:0xf
	s_nop 1
	v_mov_b32_dpp v90, v87 row_mirror row_mask:0xf bank_mask:0xf
	v_mul_f32_e32 v98, v0, v86
	global_store_short_d16_hi v[76:77], v101, off
	v_lshl_add_u64 v[68:69], v[66:67], 0, s[4:5]
	s_waitcnt lgkmcnt(0)
	v_add_f32_e32 v91, v96, v99
	s_waitcnt lgkmcnt(0)
	v_add_f32_e32 v86, v87, v90
	ds_swizzle_b32 v96, v91 offset:swizzle(SWAP,16)
	ds_swizzle_b32 v90, v86 offset:swizzle(SWAP,16)
	ds_swizzle_b32 v99, v98 offset:swizzle(SWAP,16)
	s_mov_b64 s[4:5], 0x19000cc0
	s_waitcnt lgkmcnt(0)
	v_add_f32_e32 v87, v91, v96
	s_waitcnt lgkmcnt(0)
	v_add_f32_e32 v86, v86, v90
	v_mov_b32_e32 v91, v87
	v_mov_b32_e32 v90, v86
	s_nop 0
	v_permlane32_swap_b32_e32 v87, v91
	v_permlane32_swap_b32_e32 v86, v90
	v_pk_add_f32 v[86:87], v[86:87], v[90:91]
	s_waitcnt lgkmcnt(0)
	v_mul_f32_e32 v76, v65, v99
	v_pk_fma_f32 v[86:87], v[86:87], s[18:19], v[70:71] op_sel_hi:[1,0,0]
	v_cndmask_b32_e64 v76, v76, -v76, s[10:11]
	v_mul_f32_e32 v90, 0x4b800000, v87
	v_cmp_gt_f32_e32 vcc, s44, v87
	v_fmac_f32_e32 v76, v64, v98
	v_lshl_add_u64 v[66:67], v[66:67], 0, s[4:5]
	v_cndmask_b32_e32 v87, v87, v90, vcc
	v_rsq_f32_e32 v87, v87
	v_bfe_u32 v90, v76, 16, 1
	v_add3_u32 v76, v76, v90, s13
	global_store_short_d16_hi v[88:89], v76, off
	v_mul_f32_e32 v77, 0x45800000, v87
	v_cndmask_b32_e32 v77, v87, v77, vcc
	v_mul_f32_e32 v77, v77, v97
	v_mul_f32_e32 v77, v0, v77
	ds_swizzle_b32 v87, v77 offset:swizzle(SWAP,16)
	v_mul_f32_e32 v89, v83, v83
	s_nop 1
	v_mov_b32_dpp v89, v89 quad_perm:[1,0,3,2] row_mask:0xf bank_mask:0xf
	v_mul_f32_e32 v88, 0x4b800000, v86
	v_cmp_gt_f32_e32 vcc, s44, v86
	s_waitcnt lgkmcnt(0)
; __device__ __forceinline__ float bf2f(bf16_t v) { return __uint_as_float((unsigned)v << 16); }
; __device__ __forceinline__ unsigned f2bf(float f) { unsigned u = __float_as_uint(f); return (u + 0x7fffu + ((u >> 16) & 1u)) >> 16; }
; #define SWZ_XOR(v, X) __int_as_float(__builtin_amdgcn_ds_swizzle(__float_as_int(v), ((X) << 10) | 0x1f))
; __global__ void __launch_bounds__(512, 2) fwd_kernel(Args a) {
;     ...
; #pragma unroll
;                     for (int hd = 0; hd < 8; ++hd) { const int base = hd < 6 ? 1184 + hd * 64 : 1568 + (hd - 6) * 64; float v = bf2f(rh[hd]);
;                         const float rstd = rsqrtf(wave_sum(v * v) * (1.0f / 64.0f) + EPS); v = v * rstd * (hd < 6 ? gq : gk);
;                         const float p = SWZ_XOR(v, 16); const float ov = (lane & 16) ? (p * cs[1] + v * cs[0]) : (v * cs[0] - p * cs[1]);
;                         z[base + lane] = (bf16_t)f2bf(ov); }
	v_mul_f32_e32 v76, v65, v87
	v_lshlrev_b32_e32 v87, 16, v84
	v_mul_f32_e32 v84, v87, v87
	s_nop 1
	v_mov_b32_dpp v84, v84 quad_perm:[1,0,3,2] row_mask:0xf bank_mask:0xf
	s_waitcnt lgkmcnt(0)
	v_fmac_f32_e32 v89, v83, v83
	v_cndmask_b32_e32 v86, v86, v88, vcc
	s_nop 1
	v_mov_b32_dpp v88, v89 quad_perm:[2,3,0,1] row_mask:0xf bank_mask:0xf
	v_cndmask_b32_e64 v76, v76, -v76, s[10:11]
	s_waitcnt lgkmcnt(0)
	v_fmac_f32_e32 v84, v87, v87
	s_nop 1
	v_mov_b32_dpp v90, v84 quad_perm:[2,3,0,1] row_mask:0xf bank_mask:0xf
	v_fmac_f32_e32 v76, v64, v77
	v_bfe_u32 v77, v76, 16, 1
	v_add3_u32 v91, v76, v77, s13
	s_waitcnt lgkmcnt(0)
	v_add_f32_e32 v77, v89, v88
	s_waitcnt lgkmcnt(0)
	v_add_f32_e32 v84, v84, v90
	v_rsq_f32_e32 v86, v86
	s_nop 1
	v_mov_b32_dpp v90, v84 row_half_mirror row_mask:0xf bank_mask:0xf
	s_nop 1
	v_mov_b32_dpp v88, v77 row_half_mirror row_mask:0xf bank_mask:0xf
	v_lshl_add_u64 v[6:7], v[6:7], 0, s[76:77]
	v_mul_f32_e32 v76, 0x45800000, v86
	v_cndmask_b32_e32 v76, v86, v76, vcc
	s_waitcnt lgkmcnt(0)
	v_add_f32_e32 v84, v84, v90
	s_waitcnt lgkmcnt(0)
	v_add_f32_e32 v77, v77, v88
	s_nop 1
	v_mov_b32_dpp v89, v84 row_mirror row_mask:0xf bank_mask:0xf
	v_mul_f32_e32 v76, v76, v85
	s_nop 1
	v_mov_b32_dpp v85, v77 row_mirror row_mask:0xf bank_mask:0xf
	v_mul_f32_e32 v88, v0, v76
	s_waitcnt lgkmcnt(0)
	v_add_f32_e32 v84, v84, v89
	ds_swizzle_b32 v86, v84 offset:swizzle(SWAP,16)
	s_waitcnt lgkmcnt(0)
	v_add_f32_e32 v76, v77, v85
	ds_swizzle_b32 v90, v76 offset:swizzle(SWAP,16)
	ds_swizzle_b32 v89, v88 offset:swizzle(SWAP,16)
	s_waitcnt lgkmcnt(0)
	v_add_f32_e32 v77, v84, v86
	v_mov_b32_e32 v85, v77
	s_waitcnt lgkmcnt(0)
	v_add_f32_e32 v76, v76, v90
	v_mov_b32_e32 v84, v76
	v_permlane32_swap_b32_e32 v77, v85
	s_nop 0
	v_permlane32_swap_b32_e32 v76, v84
	v_pk_add_f32 v[76:77], v[76:77], v[84:85]
	v_pk_fma_f32 v[76:77], v[76:77], s[18:19], v[70:71] op_sel_hi:[1,0,0]
	v_mul_f32_e32 v84, 0x4b800000, v77
	v_cmp_gt_f32_e32 vcc, s44, v77
	v_cndmask_b32_e32 v77, v77, v84, vcc
	v_rsq_f32_e32 v77, v77
	s_waitcnt lgkmcnt(0)
	v_mul_f32_e32 v84, v65, v89
	v_cndmask_b32_e64 v84, v84, -v84, s[10:11]
	v_fmac_f32_e32 v84, v64, v88
	v_mul_f32_e32 v85, 0x45800000, v77
	v_cndmask_b32_e32 v77, v77, v85, vcc
	v_mul_f32_e32 v77, v77, v87
	v_mul_f32_e32 v77, v0, v77
	ds_swizzle_b32 v85, v77 offset:swizzle(SWAP,16)
	v_bfe_u32 v86, v84, 16, 1
	v_add3_u32 v84, v84, v86, s13
	global_store_short_d16_hi v[94:95], v84, off
	v_cmp_gt_f32_e32 vcc, s44, v76
	s_waitcnt lgkmcnt(0)
	v_mul_f32_e32 v84, v65, v85
	v_cndmask_b32_e64 v84, v84, -v84, s[10:11]
	v_fmac_f32_e32 v84, v64, v77
	v_bfe_u32 v77, v84, 16, 1
	v_add3_u32 v77, v84, v77, s13
	v_mul_f32_e32 v84, 0x4b800000, v76
	v_cndmask_b32_e32 v76, v76, v84, vcc
	v_mul_f32_e32 v84, v82, v82
	s_nop 1
	v_mov_b32_dpp v84, v84 quad_perm:[1,0,3,2] row_mask:0xf bank_mask:0xf
	v_mul_f32_e32 v85, v81, v81
	s_nop 1
	v_mov_b32_dpp v85, v85 quad_perm:[1,0,3,2] row_mask:0xf bank_mask:0xf
	global_store_short_d16_hi v[74:75], v77, off
	v_rsq_f32_e32 v76, v76
	s_waitcnt lgkmcnt(0)
	v_fmac_f32_e32 v84, v82, v82
	s_nop 1
	v_mov_b32_dpp v86, v84 quad_perm:[2,3,0,1] row_mask:0xf bank_mask:0xf
	s_waitcnt lgkmcnt(0)
	v_fmac_f32_e32 v85, v81, v81
	s_nop 1
	v_mov_b32_dpp v75, v85 quad_perm:[2,3,0,1] row_mask:0xf bank_mask:0xf
	v_mul_f32_e32 v74, 0x45800000, v76
	v_cndmask_b32_e32 v74, v76, v74, vcc
	s_waitcnt lgkmcnt(0)
	v_add_f32_e32 v77, v84, v86
	s_nop 1
	v_mov_b32_dpp v84, v77 row_half_mirror row_mask:0xf bank_mask:0xf
	s_waitcnt lgkmcnt(0)
	v_add_f32_e32 v75, v85, v75
	s_nop 1
	v_mov_b32_dpp v76, v75 row_half_mirror row_mask:0xf bank_mask:0xf
	v_mul_f32_e32 v74, v74, v83
	global_store_short_d16_hi v[92:93], v91, off
	s_waitcnt lgkmcnt(0)
	v_add_f32_e32 v77, v77, v84
	v_mul_f32_e32 v84, v0, v74
	ds_swizzle_b32 v74, v84 offset:swizzle(SWAP,16)
	s_waitcnt lgkmcnt(0)
	v_add_f32_e32 v75, v75, v76
	s_nop 1
	v_mov_b32_dpp v83, v77 row_mirror row_mask:0xf bank_mask:0xf
	s_nop 1
	v_mov_b32_dpp v76, v75 row_mirror row_mask:0xf bank_mask:0xf
	s_waitcnt lgkmcnt(0)
	v_mul_f32_e32 v74, v65, v74
	v_cndmask_b32_e64 v85, v74, -v74, s[10:11]
	s_waitcnt lgkmcnt(0)
	v_add_f32_e32 v77, v77, v83
	s_waitcnt lgkmcnt(0)
	v_add_f32_e32 v74, v75, v76
	ds_swizzle_b32 v83, v77 offset:swizzle(SWAP,16)
	ds_swizzle_b32 v76, v74 offset:swizzle(SWAP,16)
	v_fmac_f32_e32 v85, v64, v84
	s_waitcnt lgkmcnt(0)
	v_add_f32_e32 v75, v77, v83
	s_waitcnt lgkmcnt(0)
	v_add_f32_e32 v74, v74, v76
	v_mov_b32_e32 v77, v75
	v_mov_b32_e32 v76, v74
	s_nop 0
	v_permlane32_swap_b32_e32 v75, v77
	v_permlane32_swap_b32_e32 v74, v76
	v_pk_add_f32 v[74:75], v[74:75], v[76:77]
	s_nop 0
	v_pk_fma_f32 v[70:71], v[74:75], s[18:19], v[70:71] op_sel_hi:[1,0,0]
	s_nop 0
	v_mul_f32_e32 v74, 0x4b800000, v71
	v_cmp_gt_f32_e32 vcc, s44, v71
	v_mul_f32_e32 v76, 0x4b800000, v70
	s_nop 0
	v_cndmask_b32_e32 v71, v71, v74, vcc
	v_rsq_f32_e32 v71, v71
	v_bfe_u32 v74, v85, 16, 1
	v_add3_u32 v74, v85, v74, s13
	global_store_short_d16_hi v[72:73], v74, off
	v_mul_f32_e32 v75, 0x45800000, v71
	v_cndmask_b32_e32 v71, v71, v75, vcc
	v_cmp_gt_f32_e32 vcc, s44, v70
	v_mul_f32_e32 v71, v71, v82
	v_mul_f32_e32 v71, v28, v71
	v_cndmask_b32_e32 v70, v70, v76, vcc
	v_rsq_f32_e32 v70, v70
	ds_swizzle_b32 v75, v71 offset:swizzle(SWAP,16)
	v_mul_f32_e32 v73, 0x45800000, v70
	v_cndmask_b32_e32 v70, v70, v73, vcc
	v_mul_f32_e32 v70, v70, v81
	v_mul_f32_e32 v70, v28, v70
	ds_swizzle_b32 v73, v70 offset:swizzle(SWAP,16)
	s_waitcnt lgkmcnt(0)
	v_mul_f32_e32 v72, v65, v75
	v_cndmask_b32_e64 v72, v72, -v72, s[10:11]
	v_fmac_f32_e32 v72, v64, v71
	v_bfe_u32 v71, v72, 16, 1
	s_waitcnt lgkmcnt(0)
	v_mul_f32_e32 v65, v65, v73
	v_cndmask_b32_e64 v65, v65, -v65, s[10:11]
	v_fmac_f32_e32 v65, v64, v70
	v_bfe_u32 v64, v65, 16, 1
	v_add3_u32 v71, v72, v71, s13
	v_add3_u32 v64, v65, v64, s13
	global_store_short_d16_hi v[68:69], v71, off
	global_store_short_d16_hi v[66:67], v64, off
	s_branch .Lzp_loop
; __device__ __forceinline__ float bf2f(bf16_t v) { return __uint_as_float((unsigned)v << 16); }
; __device__ __forceinline__ unsigned f2bf(float f) { unsigned u = __float_as_uint(f); return (u + 0x7fffu + ((u >> 16) & 1u)) >> 16; }
; __device__ __forceinline__ unsigned pk2(float lo, float hi) { f32x2_t v = {lo, hi}; bf16x2_t b = __builtin_convertvector(v, bf16x2_t); return __builtin_bit_cast(unsigned, b); }
; #define SWZ_XOR(v, X) __int_as_float(__builtin_amdgcn_ds_swizzle(__float_as_int(v), ((X) << 10) | 0x1f))
; __global__ void __launch_bounds__(512, 2) fwd_kernel(Args a) {
;     ...
;                     { const float x1 = bf2f(ra1), x2 = bf2f(ra2);
;                       z[basea + ia] = (bf16_t)f2bf(x1 * csa[0] - x2 * csa[1]); z[basea + 4 + ia] = (bf16_t)f2bf(x1 * csa[1] + x2 * csa[0]); }
;                     { const float v0 = __uint_as_float(wq.x << 16), v1 = __uint_as_float(wq.x & 0xffff0000u), v2 = __uint_as_float(wq.y << 16), v3 = __uint_as_float(wq.y & 0xffff0000u);
;                       const float rstd = rsqrtf(wave_sum((v0 * v0 + v1 * v1) + (v2 * v2 + v3 * v3)) * (1.0f / 256.0f) + EPS);
;                       u32x2 o; o.x = pk2(v0 * rstd, v1 * rstd); o.y = pk2(v2 * rstd, v3 * rstd); *(u32x2*)(z + 768 + 4 * lane) = o; }
;                     { const float v0 = __uint_as_float(wkv << 16), v1 = __uint_as_float(wkv & 0xffff0000u);
;                       const float rstd = rsqrtf(wave_sum(v0 * v0 + v1 * v1) * (1.0f / 128.0f) + EPS);
;                       *(unsigned*)(z + 1024 + 2 * lane) = pk2(v0 * rstd, v1 * rstd); }
;                     if (lane < 16) { const float x1 = bf2f(rk1), x2 = bf2f(rk2);
;                         *(unsigned*)(KPE + (size_t)m * 32 + 2 * lane) = pk2(x1 * csk[0] - x2 * csk[1], x1 * csk[1] + x2 * csk[0]); }
; #pragma unroll
;                     for (int hd = 0; hd < 8; ++hd) { const int base = hd < 6 ? 1184 + hd * 64 : 1568 + (hd - 6) * 64; float v = bf2f(rh[hd]);
;                         const float rstd = rsqrtf(wave_sum(v * v) * (1.0f / 64.0f) + EPS); v = v * rstd * (hd < 6 ? gq : gk);
;                         const float p = SWZ_XOR(v, 16); const float ov = (lane & 16) ? (p * cs[1] + v * cs[0]) : (v * cs[0] - p * cs[1]);
;                         z[base + lane] = (bf16_t)f2bf(ov); }
.Lzp_last:
	s_waitcnt vmcnt(13)
	v_lshlrev_b32_e32 v94, 16, v94
	v_lshlrev_b32_e32 v95, 16, v95
	v_mul_f32_e32 v96, v77, v95
	v_fma_f32 v96, v76, v94, -v96
	v_mul_f32_e32 v76, v76, v95
	v_fmac_f32_e32 v76, v77, v94
	v_bfe_u32 v97, v96, 16, 1
	v_bfe_u32 v77, v76, 16, 1
	v_add3_u32 v96, v96, v97, s13
	v_add3_u32 v76, v76, v77, s13
	global_store_short_d16_hi v[92:93], v96, off
	global_store_short_d16_hi v[92:93], v76, off offset:8
	v_and_b32_e32 v77, 0xffff0000, v75
	v_and_b32_e32 v93, 0xffff0000, v74
	v_lshlrev_b32_e32 v76, 16, v75
	v_lshlrev_b32_e32 v92, 16, v74
	v_mov_b32_e32 v94, v93
	v_mov_b32_e32 v95, v77
	v_mov_b32_e32 v74, v92
	v_mov_b32_e32 v75, v76
	v_pk_mul_f32 v[94:95], v[94:95], v[94:95]
	v_lshlrev_b32_e32 v96, 16, v91
	v_pk_fma_f32 v[74:75], v[74:75], v[74:75], v[94:95]
	v_and_b32_e32 v97, 0xffff0000, v91
	v_add_f32_e32 v74, v74, v75
	s_nop 1
	v_mov_b32_dpp v75, v74 quad_perm:[1,0,3,2] row_mask:0xf bank_mask:0xf
	v_pk_mul_f32 v[98:99], v[96:97], v[96:97]
	s_waitcnt lgkmcnt(0)
	v_add_f32_e32 v74, v74, v75
	s_nop 1
	v_mov_b32_dpp v75, v74 quad_perm:[2,3,0,1] row_mask:0xf bank_mask:0xf
	s_waitcnt lgkmcnt(0)
	v_add_f32_e32 v74, v74, v75
	s_nop 1
	v_mov_b32_dpp v75, v74 row_half_mirror row_mask:0xf bank_mask:0xf
	s_waitcnt lgkmcnt(0)
	v_add_f32_e32 v74, v74, v75
	s_nop 1
	v_mov_b32_dpp v75, v74 row_mirror row_mask:0xf bank_mask:0xf
	s_waitcnt lgkmcnt(0)
	v_add_f32_e32 v74, v74, v75
	ds_swizzle_b32 v75, v74 offset:swizzle(SWAP,16)
	s_waitcnt lgkmcnt(0)
	v_add_f32_e32 v75, v74, v75
	v_add_f32_e32 v74, v98, v99
	s_nop 1
	v_mov_b32_dpp v91, v74 quad_perm:[1,0,3,2] row_mask:0xf bank_mask:0xf
	v_mov_b32_e32 v95, v75
	s_nop 1
	v_permlane32_swap_b32_e32 v75, v95
	s_waitcnt lgkmcnt(0)
	v_add_f32_e32 v74, v74, v91
	s_nop 1
	v_mov_b32_dpp v91, v74 quad_perm:[2,3,0,1] row_mask:0xf bank_mask:0xf
	s_waitcnt lgkmcnt(0)
	v_add_f32_e32 v74, v74, v91
	s_nop 1
	v_mov_b32_dpp v91, v74 row_half_mirror row_mask:0xf bank_mask:0xf
	s_waitcnt lgkmcnt(0)
	v_add_f32_e32 v74, v74, v91
	s_nop 1
	v_mov_b32_dpp v91, v74 row_mirror row_mask:0xf bank_mask:0xf
	s_waitcnt lgkmcnt(0)
	v_add_f32_e32 v74, v74, v91
	ds_swizzle_b32 v91, v74 offset:swizzle(SWAP,16)
	s_waitcnt lgkmcnt(0)
	v_add_f32_e32 v74, v74, v91
	v_mov_b32_e32 v94, v74
	s_nop 1
	v_permlane32_swap_b32_e32 v74, v94
	v_pk_add_f32 v[74:75], v[74:75], v[94:95]
	s_nop 0
	v_pk_fma_f32 v[74:75], v[74:75], s[16:17], v[200:201] op_sel_hi:[1,1,0]
	s_nop 0
	v_mul_f32_e32 v91, 0x4b800000, v75
	v_cmp_gt_f32_e64 s[14:15], s44, v75
	v_cmp_gt_f32_e32 vcc, s44, v74
	s_nop 0
	v_cndmask_b32_e64 v75, v75, v91, s[14:15]
	v_rsq_f32_e32 v75, v75
	s_nop 0
	v_mul_f32_e32 v91, 0x45800000, v75
	v_cndmask_b32_e64 v94, v75, v91, s[14:15]
	v_pk_mul_f32 v[92:93], v[94:95], v[92:93] op_sel_hi:[0,1]
	v_pk_mul_f32 v[76:77], v[94:95], v[76:77] op_sel_hi:[0,1]
	v_cvt_pk_bf16_f32 v92, v92, v93
	v_cvt_pk_bf16_f32 v93, v76, v77
	global_store_dwordx2 v[72:73], v[92:93], off
	v_mul_f32_e32 v72, 0x4b800000, v74
	v_cndmask_b32_e32 v72, v74, v72, vcc
	v_rsq_f32_e32 v72, v72
	s_nop 0
	v_mul_f32_e32 v73, 0x45800000, v72
	v_cndmask_b32_e32 v72, v72, v73, vcc
	v_pk_mul_f32 v[72:73], v[72:73], v[96:97] op_sel_hi:[0,1]
	v_cvt_pk_bf16_f32 v72, v72, v73
	global_store_dword v[68:69], v72, off
	s_and_saveexec_b64 s[4:5], s[8:9]
	s_cbranch_execz .Lzp_x_cbl
	v_lshlrev_b32_e32 v72, 16, v90
	v_lshlrev_b32_e32 v68, 16, v89
	v_pk_mul_f32 v[72:73], v[70:71], v[72:73] op_sel:[1,0] op_sel_hi:[0,0]
	v_readlane_b32 s36, v252, 21
	v_pk_fma_f32 v[74:75], v[70:71], v[68:69], v[72:73] neg_lo:[0,0,1] neg_hi:[0,0,1]
	v_pk_fma_f32 v[68:69], v[70:71], v[68:69], v[72:73] op_sel_hi:[1,0,1]
	v_readlane_b32 s38, v252, 23
	v_readlane_b32 s39, v252, 24
	v_cvt_pk_bf16_f32 v70, v74, v69
	v_readlane_b32 s37, v252, 22
	v_lshl_add_u64 v[68:69], s[38:39], 0, v[6:7]
	global_store_dword v[68:69], v70, off
.Lzp_x_cbl:
	s_or_b64 exec, exec, s[4:5]
	v_lshlrev_b32_e32 v96, 16, v88
	v_lshlrev_b32_e32 v87, 16, v87
	v_mul_f32_e32 v68, v96, v96
	v_mul_f32_e32 v69, v87, v87
	s_nop 1
	v_mov_b32_dpp v68, v68 quad_perm:[1,0,3,2] row_mask:0xf bank_mask:0xf
	s_nop 1
	v_mov_b32_dpp v69, v69 quad_perm:[1,0,3,2] row_mask:0xf bank_mask:0xf
	s_mov_b32 s0, 0x358637bd
	v_lshlrev_b32_e32 v97, 16, v86
	v_lshlrev_b32_e32 v85, 16, v85
	s_waitcnt lgkmcnt(0)
	v_fmac_f32_e32 v68, v96, v96
	s_waitcnt lgkmcnt(0)
	v_fmac_f32_e32 v69, v87, v87
	s_nop 1
	v_mov_b32_dpp v70, v68 quad_perm:[2,3,0,1] row_mask:0xf bank_mask:0xf
	s_nop 1
	v_mov_b32_dpp v71, v69 quad_perm:[2,3,0,1] row_mask:0xf bank_mask:0xf
	v_mul_f32_e32 v99, v85, v85
	s_nop 1
	v_mov_b32_dpp v99, v99 quad_perm:[1,0,3,2] row_mask:0xf bank_mask:0xf
	s_mov_b64 s[4:5], 0x19000940
	s_waitcnt lgkmcnt(0)
	v_add_f32_e32 v68, v68, v70
	s_waitcnt lgkmcnt(0)
	v_add_f32_e32 v69, v69, v71
	s_nop 1
	v_mov_b32_dpp v70, v68 row_half_mirror row_mask:0xf bank_mask:0xf
	s_nop 1
	v_mov_b32_dpp v71, v69 row_half_mirror row_mask:0xf bank_mask:0xf
	s_waitcnt lgkmcnt(0)
	v_fmac_f32_e32 v99, v85, v85
	v_lshl_add_u64 v[76:77], v[66:67], 0, s[4:5]
	s_mov_b64 s[4:5], 0x190009c0
	s_waitcnt lgkmcnt(0)
	v_add_f32_e32 v68, v68, v70
	s_waitcnt lgkmcnt(0)
	v_add_f32_e32 v69, v69, v71
	s_nop 1
	v_mov_b32_dpp v70, v68 row_mirror row_mask:0xf bank_mask:0xf
	s_nop 1
	v_mov_b32_dpp v71, v69 row_mirror row_mask:0xf bank_mask:0xf
	v_lshl_add_u64 v[88:89], v[66:67], 0, s[4:5]
	v_lshlrev_b32_e32 v83, 16, v83
	s_mov_b64 s[4:5], 0x19000a40
	s_waitcnt lgkmcnt(0)
	v_add_f32_e32 v68, v68, v70
	s_waitcnt lgkmcnt(0)
	v_add_f32_e32 v72, v69, v71
	ds_swizzle_b32 v69, v68 offset:swizzle(SWAP,16)
	ds_swizzle_b32 v73, v72 offset:swizzle(SWAP,16)
	v_mov_b64_e32 v[70:71], s[0:1]
	v_lshl_add_u64 v[92:93], v[66:67], 0, s[4:5]
	s_mov_b64 s[4:5], 0x19000ac0
	s_waitcnt lgkmcnt(0)
; __device__ __forceinline__ float bf2f(bf16_t v) { return __uint_as_float((unsigned)v << 16); }
; __device__ __forceinline__ unsigned f2bf(float f) { unsigned u = __float_as_uint(f); return (u + 0x7fffu + ((u >> 16) & 1u)) >> 16; }
; #define SWZ_XOR(v, X) __int_as_float(__builtin_amdgcn_ds_swizzle(__float_as_int(v), ((X) << 10) | 0x1f))
; __global__ void __launch_bounds__(512, 2) fwd_kernel(Args a) {
;     ...
; #pragma unroll
;                     for (int hd = 0; hd < 8; ++hd) { const int base = hd < 6 ? 1184 + hd * 64 : 1568 + (hd - 6) * 64; float v = bf2f(rh[hd]);
;                         const float rstd = rsqrtf(wave_sum(v * v) * (1.0f / 64.0f) + EPS); v = v * rstd * (hd < 6 ? gq : gk);
;                         const float p = SWZ_XOR(v, 16); const float ov = (lane & 16) ? (p * cs[1] + v * cs[0]) : (v * cs[0] - p * cs[1]);
;                         z[base + lane] = (bf16_t)f2bf(ov); }
	v_add_f32_e32 v69, v68, v69
	s_waitcnt lgkmcnt(0)
	v_add_f32_e32 v68, v72, v73
	v_mov_b32_e32 v73, v69
	v_mov_b32_e32 v72, v68
	s_nop 0
	v_permlane32_swap_b32_e32 v69, v73
	v_permlane32_swap_b32_e32 v68, v72
	v_pk_add_f32 v[68:69], v[68:69], v[72:73]
	v_lshl_add_u64 v[94:95], v[66:67], 0, s[4:5]
	v_pk_fma_f32 v[90:91], v[68:69], s[18:19], v[70:71] op_sel_hi:[1,0,0]
	v_lshlrev_b32_e32 v82, 16, v82
	v_mul_f32_e32 v68, 0x4b800000, v91
	v_cmp_gt_f32_e32 vcc, s44, v91
	v_mul_f32_e32 v98, 0x4b800000, v90
	v_lshlrev_b32_e32 v81, 16, v81
	v_cndmask_b32_e32 v68, v91, v68, vcc
	v_rsq_f32_e32 v68, v68
	s_mov_b64 s[4:5], 0x19000b40
	v_lshl_add_u64 v[74:75], v[66:67], 0, s[4:5]
	s_mov_b64 s[4:5], 0x19000bc0
	v_mul_f32_e32 v69, 0x45800000, v68
	v_cndmask_b32_e32 v68, v68, v69, vcc
	v_mul_f32_e32 v68, v68, v96
	v_mul_f32_e32 v91, v0, v68
	ds_swizzle_b32 v96, v91 offset:swizzle(SWAP,16)
	v_cmp_gt_f32_e32 vcc, s44, v90
	v_lshl_add_u64 v[72:73], v[66:67], 0, s[4:5]
	s_mov_b64 s[4:5], 0x19000c40
	v_cndmask_b32_e32 v90, v90, v98, vcc
	s_waitcnt lgkmcnt(0)
	v_mul_f32_e32 v86, v65, v96
	v_mul_f32_e32 v96, v97, v97
	s_nop 1
	v_mov_b32_dpp v96, v96 quad_perm:[1,0,3,2] row_mask:0xf bank_mask:0xf
	s_nop 1
	v_mov_b32_dpp v98, v99 quad_perm:[2,3,0,1] row_mask:0xf bank_mask:0xf
	v_cndmask_b32_e64 v86, v86, -v86, s[10:11]
	v_fmac_f32_e32 v86, v64, v91
	v_bfe_u32 v91, v86, 16, 1
	s_waitcnt lgkmcnt(0)
	v_fmac_f32_e32 v96, v97, v97
	s_nop 1
	v_mov_b32_dpp v100, v96 quad_perm:[2,3,0,1] row_mask:0xf bank_mask:0xf
	v_rsq_f32_e32 v90, v90
	v_add3_u32 v101, v86, v91, s13
	s_waitcnt lgkmcnt(0)
	v_add_f32_e32 v91, v99, v98
	s_nop 1
	v_mov_b32_dpp v98, v91 row_half_mirror row_mask:0xf bank_mask:0xf
	s_waitcnt lgkmcnt(0)
	v_add_f32_e32 v96, v96, v100
	s_nop 1
	v_mov_b32_dpp v100, v96 row_half_mirror row_mask:0xf bank_mask:0xf
	v_mul_f32_e32 v86, 0x45800000, v90
	v_cndmask_b32_e32 v86, v90, v86, vcc
	v_mul_f32_e32 v86, v86, v87
	s_waitcnt lgkmcnt(0)
	v_add_f32_e32 v87, v91, v98
	s_waitcnt lgkmcnt(0)
	v_add_f32_e32 v96, v96, v100
	s_nop 1
	v_mov_b32_dpp v99, v96 row_mirror row_mask:0xf bank_mask:0xf
	s_nop 1
	v_mov_b32_dpp v90, v87 row_mirror row_mask:0xf bank_mask:0xf
	v_mul_f32_e32 v98, v0, v86
	global_store_short_d16_hi v[76:77], v101, off
	v_lshl_add_u64 v[68:69], v[66:67], 0, s[4:5]
	s_waitcnt lgkmcnt(0)
	v_add_f32_e32 v91, v96, v99
	s_waitcnt lgkmcnt(0)
	v_add_f32_e32 v86, v87, v90
	ds_swizzle_b32 v96, v91 offset:swizzle(SWAP,16)
	ds_swizzle_b32 v90, v86 offset:swizzle(SWAP,16)
	ds_swizzle_b32 v99, v98 offset:swizzle(SWAP,16)
	s_mov_b64 s[4:5], 0x19000cc0
	s_waitcnt lgkmcnt(0)
	v_add_f32_e32 v87, v91, v96
	s_waitcnt lgkmcnt(0)
	v_add_f32_e32 v86, v86, v90
	v_mov_b32_e32 v91, v87
	v_mov_b32_e32 v90, v86
	s_nop 0
	v_permlane32_swap_b32_e32 v87, v91
	v_permlane32_swap_b32_e32 v86, v90
	v_pk_add_f32 v[86:87], v[86:87], v[90:91]
	s_waitcnt lgkmcnt(0)
	v_mul_f32_e32 v76, v65, v99
	v_pk_fma_f32 v[86:87], v[86:87], s[18:19], v[70:71] op_sel_hi:[1,0,0]
	v_cndmask_b32_e64 v76, v76, -v76, s[10:11]
	v_mul_f32_e32 v90, 0x4b800000, v87
	v_cmp_gt_f32_e32 vcc, s44, v87
	v_fmac_f32_e32 v76, v64, v98
	v_lshl_add_u64 v[66:67], v[66:67], 0, s[4:5]
	v_cndmask_b32_e32 v87, v87, v90, vcc
	v_rsq_f32_e32 v87, v87
	v_bfe_u32 v90, v76, 16, 1
	v_add3_u32 v76, v76, v90, s13
	global_store_short_d16_hi v[88:89], v76, off
	v_mul_f32_e32 v77, 0x45800000, v87
	v_cndmask_b32_e32 v77, v87, v77, vcc
	v_mul_f32_e32 v77, v77, v97
	v_mul_f32_e32 v77, v0, v77
	ds_swizzle_b32 v87, v77 offset:swizzle(SWAP,16)
	v_mul_f32_e32 v89, v83, v83
	s_nop 1
	v_mov_b32_dpp v89, v89 quad_perm:[1,0,3,2] row_mask:0xf bank_mask:0xf
	v_mul_f32_e32 v88, 0x4b800000, v86
	v_cmp_gt_f32_e32 vcc, s44, v86
	s_waitcnt lgkmcnt(0)
	v_mul_f32_e32 v76, v65, v87
	v_lshlrev_b32_e32 v87, 16, v84
	v_mul_f32_e32 v84, v87, v87
	s_nop 1
	v_mov_b32_dpp v84, v84 quad_perm:[1,0,3,2] row_mask:0xf bank_mask:0xf
	s_waitcnt lgkmcnt(0)
	v_fmac_f32_e32 v89, v83, v83
	v_cndmask_b32_e32 v86, v86, v88, vcc
	s_nop 1
	v_mov_b32_dpp v88, v89 quad_perm:[2,3,0,1] row_mask:0xf bank_mask:0xf
	v_cndmask_b32_e64 v76, v76, -v76, s[10:11]
	s_waitcnt lgkmcnt(0)
	v_fmac_f32_e32 v84, v87, v87
	s_nop 1
	v_mov_b32_dpp v90, v84 quad_perm:[2,3,0,1] row_mask:0xf bank_mask:0xf
	v_fmac_f32_e32 v76, v64, v77
	v_bfe_u32 v77, v76, 16, 1
	v_add3_u32 v91, v76, v77, s13
	s_waitcnt lgkmcnt(0)
	v_add_f32_e32 v77, v89, v88
	s_waitcnt lgkmcnt(0)
	v_add_f32_e32 v84, v84, v90
	v_rsq_f32_e32 v86, v86
	s_nop 1
	v_mov_b32_dpp v90, v84 row_half_mirror row_mask:0xf bank_mask:0xf
	s_nop 1
	v_mov_b32_dpp v88, v77 row_half_mirror row_mask:0xf bank_mask:0xf
	v_lshl_add_u64 v[6:7], v[6:7], 0, s[76:77]
	v_mul_f32_e32 v76, 0x45800000, v86
	v_cndmask_b32_e32 v76, v86, v76, vcc
	s_waitcnt lgkmcnt(0)
	v_add_f32_e32 v84, v84, v90
	s_waitcnt lgkmcnt(0)
; __device__ __forceinline__ float bf2f(bf16_t v) { return __uint_as_float((unsigned)v << 16); }
; __device__ __forceinline__ unsigned f2bf(float f) { unsigned u = __float_as_uint(f); return (u + 0x7fffu + ((u >> 16) & 1u)) >> 16; }
; #define SWZ_XOR(v, X) __int_as_float(__builtin_amdgcn_ds_swizzle(__float_as_int(v), ((X) << 10) | 0x1f))
; __global__ void __launch_bounds__(512, 2) fwd_kernel(Args a) {
;     ...
; #pragma unroll
;                     for (int hd = 0; hd < 8; ++hd) { const int base = hd < 6 ? 1184 + hd * 64 : 1568 + (hd - 6) * 64; float v = bf2f(rh[hd]);
;                         const float rstd = rsqrtf(wave_sum(v * v) * (1.0f / 64.0f) + EPS); v = v * rstd * (hd < 6 ? gq : gk);
;                         const float p = SWZ_XOR(v, 16); const float ov = (lane & 16) ? (p * cs[1] + v * cs[0]) : (v * cs[0] - p * cs[1]);
;                         z[base + lane] = (bf16_t)f2bf(ov); }
	v_add_f32_e32 v77, v77, v88
	s_nop 1
	v_mov_b32_dpp v89, v84 row_mirror row_mask:0xf bank_mask:0xf
	v_mul_f32_e32 v76, v76, v85
	s_nop 1
	v_mov_b32_dpp v85, v77 row_mirror row_mask:0xf bank_mask:0xf
	v_mul_f32_e32 v88, v0, v76
	s_waitcnt lgkmcnt(0)
	v_add_f32_e32 v84, v84, v89
	ds_swizzle_b32 v86, v84 offset:swizzle(SWAP,16)
	s_waitcnt lgkmcnt(0)
	v_add_f32_e32 v76, v77, v85
	ds_swizzle_b32 v90, v76 offset:swizzle(SWAP,16)
	ds_swizzle_b32 v89, v88 offset:swizzle(SWAP,16)
	s_waitcnt lgkmcnt(0)
	v_add_f32_e32 v77, v84, v86
	v_mov_b32_e32 v85, v77
	s_waitcnt lgkmcnt(0)
	v_add_f32_e32 v76, v76, v90
	v_mov_b32_e32 v84, v76
	v_permlane32_swap_b32_e32 v77, v85
	s_nop 0
	v_permlane32_swap_b32_e32 v76, v84
	v_pk_add_f32 v[76:77], v[76:77], v[84:85]
	v_pk_fma_f32 v[76:77], v[76:77], s[18:19], v[70:71] op_sel_hi:[1,0,0]
	v_mul_f32_e32 v84, 0x4b800000, v77
	v_cmp_gt_f32_e32 vcc, s44, v77
	v_cndmask_b32_e32 v77, v77, v84, vcc
	v_rsq_f32_e32 v77, v77
	s_waitcnt lgkmcnt(0)
	v_mul_f32_e32 v84, v65, v89
	v_cndmask_b32_e64 v84, v84, -v84, s[10:11]
	v_fmac_f32_e32 v84, v64, v88
	v_mul_f32_e32 v85, 0x45800000, v77
	v_cndmask_b32_e32 v77, v77, v85, vcc
	v_mul_f32_e32 v77, v77, v87
	v_mul_f32_e32 v77, v0, v77
	ds_swizzle_b32 v85, v77 offset:swizzle(SWAP,16)
	v_bfe_u32 v86, v84, 16, 1
	v_add3_u32 v84, v84, v86, s13
	global_store_short_d16_hi v[94:95], v84, off
	v_cmp_gt_f32_e32 vcc, s44, v76
	s_waitcnt lgkmcnt(0)
	v_mul_f32_e32 v84, v65, v85
	v_cndmask_b32_e64 v84, v84, -v84, s[10:11]
	v_fmac_f32_e32 v84, v64, v77
	v_bfe_u32 v77, v84, 16, 1
	v_add3_u32 v77, v84, v77, s13
	v_mul_f32_e32 v84, 0x4b800000, v76
	v_cndmask_b32_e32 v76, v76, v84, vcc
	v_mul_f32_e32 v84, v82, v82
	s_nop 1
	v_mov_b32_dpp v84, v84 quad_perm:[1,0,3,2] row_mask:0xf bank_mask:0xf
	v_mul_f32_e32 v85, v81, v81
	s_nop 1
	v_mov_b32_dpp v85, v85 quad_perm:[1,0,3,2] row_mask:0xf bank_mask:0xf
	global_store_short_d16_hi v[74:75], v77, off
	v_rsq_f32_e32 v76, v76
	s_waitcnt lgkmcnt(0)
	v_fmac_f32_e32 v84, v82, v82
	s_nop 1
	v_mov_b32_dpp v86, v84 quad_perm:[2,3,0,1] row_mask:0xf bank_mask:0xf
	s_waitcnt lgkmcnt(0)
	v_fmac_f32_e32 v85, v81, v81
	s_nop 1
	v_mov_b32_dpp v75, v85 quad_perm:[2,3,0,1] row_mask:0xf bank_mask:0xf
	v_mul_f32_e32 v74, 0x45800000, v76
	v_cndmask_b32_e32 v74, v76, v74, vcc
	s_waitcnt lgkmcnt(0)
	v_add_f32_e32 v77, v84, v86
	s_nop 1
	v_mov_b32_dpp v84, v77 row_half_mirror row_mask:0xf bank_mask:0xf
	s_waitcnt lgkmcnt(0)
	v_add_f32_e32 v75, v85, v75
	s_nop 1
	v_mov_b32_dpp v76, v75 row_half_mirror row_mask:0xf bank_mask:0xf
	v_mul_f32_e32 v74, v74, v83
	global_store_short_d16_hi v[92:93], v91, off
	s_waitcnt lgkmcnt(0)
	v_add_f32_e32 v77, v77, v84
	v_mul_f32_e32 v84, v0, v74
	ds_swizzle_b32 v74, v84 offset:swizzle(SWAP,16)
	s_waitcnt lgkmcnt(0)
	v_add_f32_e32 v75, v75, v76
	s_nop 1
	v_mov_b32_dpp v83, v77 row_mirror row_mask:0xf bank_mask:0xf
	s_nop 1
	v_mov_b32_dpp v76, v75 row_mirror row_mask:0xf bank_mask:0xf
	s_waitcnt lgkmcnt(0)
	v_mul_f32_e32 v74, v65, v74
	v_cndmask_b32_e64 v85, v74, -v74, s[10:11]
	s_waitcnt lgkmcnt(0)
	v_add_f32_e32 v77, v77, v83
	s_waitcnt lgkmcnt(0)
	v_add_f32_e32 v74, v75, v76
	ds_swizzle_b32 v83, v77 offset:swizzle(SWAP,16)
	ds_swizzle_b32 v76, v74 offset:swizzle(SWAP,16)
	v_fmac_f32_e32 v85, v64, v84
	s_waitcnt lgkmcnt(0)
	v_add_f32_e32 v75, v77, v83
	s_waitcnt lgkmcnt(0)
	v_add_f32_e32 v74, v74, v76
	v_mov_b32_e32 v77, v75
	v_mov_b32_e32 v76, v74
	s_nop 0
	v_permlane32_swap_b32_e32 v75, v77
	v_permlane32_swap_b32_e32 v74, v76
	v_pk_add_f32 v[74:75], v[74:75], v[76:77]
	s_nop 0
	v_pk_fma_f32 v[70:71], v[74:75], s[18:19], v[70:71] op_sel_hi:[1,0,0]
	s_nop 0
	v_mul_f32_e32 v74, 0x4b800000, v71
	v_cmp_gt_f32_e32 vcc, s44, v71
	v_mul_f32_e32 v76, 0x4b800000, v70
	s_nop 0
	v_cndmask_b32_e32 v71, v71, v74, vcc
	v_rsq_f32_e32 v71, v71
	v_bfe_u32 v74, v85, 16, 1
	v_add3_u32 v74, v85, v74, s13
	global_store_short_d16_hi v[72:73], v74, off
	v_mul_f32_e32 v75, 0x45800000, v71
	v_cndmask_b32_e32 v71, v71, v75, vcc
	v_cmp_gt_f32_e32 vcc, s44, v70
	v_mul_f32_e32 v71, v71, v82
	v_mul_f32_e32 v71, v28, v71
	v_cndmask_b32_e32 v70, v70, v76, vcc
	v_rsq_f32_e32 v70, v70
	ds_swizzle_b32 v75, v71 offset:swizzle(SWAP,16)
	v_mul_f32_e32 v73, 0x45800000, v70
	v_cndmask_b32_e32 v70, v70, v73, vcc
	v_mul_f32_e32 v70, v70, v81
	v_mul_f32_e32 v70, v28, v70
	ds_swizzle_b32 v73, v70 offset:swizzle(SWAP,16)
	s_waitcnt lgkmcnt(0)
	v_mul_f32_e32 v72, v65, v75
	v_cndmask_b32_e64 v72, v72, -v72, s[10:11]
	v_fmac_f32_e32 v72, v64, v71
	v_bfe_u32 v71, v72, 16, 1
	s_waitcnt lgkmcnt(0)
	v_mul_f32_e32 v65, v65, v73
	v_cndmask_b32_e64 v65, v65, -v65, s[10:11]
	v_fmac_f32_e32 v65, v64, v70
	v_bfe_u32 v64, v65, 16, 1
	v_add3_u32 v71, v72, v71, s13
	v_add3_u32 v64, v65, v64, s13
	global_store_short_d16_hi v[68:69], v71, off
	global_store_short_d16_hi v[66:67], v64, off
	s_branch .LBB0_319
	s_branch .LBB0_316
